# xg (bf16 next-norm operand) epilogue stores of Wo and down GEMMs merged pairwise into dwordx4 via v_permlane16_swap; up-GEMM epilogue ssq/bias loads prefetched at unit start
# speedup vs baseline: 1.0080x; 1.0062x over previous
; #define PG8_STAGE(bufoff, gbase, voff) do { _Pragma("unroll") for (int _i = 0; _i < 2; ++_i) \
;         __builtin_amdgcn_global_load_lds((const unsigned*)((const char*)(gbase) + (voff)[_i]), (LAS unsigned*)(lds + (bufoff) + ldsw + _i * 8192), 16, 0, 0); } while (0)
; #define PG8_WAIT_V(n) asm volatile("s_waitcnt vmcnt(" #n ")" ::: "memory")
; #define PG8_BAR __builtin_amdgcn_s_barrier()
; template <class Epi, int AMODE>
; __device__ __forceinline__ void gemm_phase(LAS unsigned char* lds, const Gemm g, const StaticOrder& S, const Epi& E, int stagger_us, int tid_in) {
;     ...
;     const char* cA = Abase + (size_t)cur.pm * tstepA; const char* cB = (const char*)g.Bt + (size_t)cur.pn * tstepB;
;     PG8_STAGE(PG8_SB(0, 0), cB, voffB); PG8_STAGE(PG8_SB(0, 1), cB + hstepB, voffB); PG8_STAGE(PG8_SA(0, 0), cA, voffA); PG8_STAGE(PG8_SA(0, 1), cA + hstepA, voffA);
;     if (wr == 1) PG8_BAR;
;     PG8_WAIT_V(2); PG8_BAR;
;     PG8_STAGE(PG8_SB(1, 0), cB + kstep, voffB); PG8_STAGE(PG8_SA(1, 0), cA + kstep, voffA); PG8_STAGE(PG8_SB(1, 1), cB + hstepB + kstep, voffB);
;     PG8_WAIT_V(6); PG8_BAR;
.LBB0_1193:
	s_mul_i32 s31, s27, 0x90000
	s_mul_hi_i32 s30, s27, 0x90000
	s_add_u32 s36, s42, s31
	s_addc_u32 s37, s43, s30
	s_add_u32 s79, s36, 0x304000
	s_addc_u32 s83, s37, 0
	s_lshl_b32 s30, s27, 11
	s_ashr_i32 s31, s30, 31
	s_lshl_b64 s[30:31], s[30:31], 2
	s_waitcnt lgkmcnt(0)
	s_add_u32 s52, s6, s30
	s_addc_u32 s53, s7, s31
	s_add_u32 s85, s36, 0x308000
	s_addc_u32 s87, s37, 0
	s_lshl_b32 s6, s27, 1
	s_or_b32 s6, s6, 1
	s_mul_hi_i32 s7, s6, 0x28400
	s_mul_i32 s6, s6, 0x28400
	s_add_u32 s6, s42, s6
	s_addc_u32 s7, s43, s7
	v_bfe_u32 v19, v13, 4, 2
	s_add_u32 s54, s6, 0x100000
	v_and_b32_e32 v20, 15, v13
	v_lshlrev_b32_e32 v21, 4, v19
	v_lshlrev_b32_e32 v13, 2, v13
	s_addc_u32 s55, s7, 0
	v_lshl_or_b32 v204, s29, 6, v20
	v_lshl_or_b32 v20, v20, 6, v21
	s_lshl_b32 s6, s29, 13
	v_and_b32_e32 v13, 32, v13
	v_bitop3_b32 v21, v20, s6, v13 bitop3:0xde
	s_lshl_b32 s6, s28, 5
	s_and_b32 s27, s6, 0x60
	s_lshl_b32 s6, s27, 7
	s_add_u32 s42, s42, 0x17100000
	s_addc_u32 s43, s43, 0
	s_add_i32 m0, s66, 0x18000
	v_lshl_add_u64 v[8:9], v[8:9], 0, s[74:75]
	s_waitcnt vmcnt(2)
	s_barrier
	global_load_lds_dwordx4 v[8:9], off
	v_lshl_add_u64 v[6:7], v[6:7], 0, s[74:75]
	s_add_i32 m0, s66, 0x1a000
	s_add_i32 s91, s66, 0x8000
	s_add_i32 s96, s66, 0xa000
	v_bitop3_b32 v205, v20, s6, v13 bitop3:0xde
	global_load_lds_dwordx4 v[6:7], off
	v_lshl_add_u64 v[2:3], v[2:3], 0, s[74:75]
	s_mov_b32 m0, s91
	s_add_u32 s6, s4, 0x80080
	global_load_lds_dwordx4 v[2:3], off
	v_lshl_add_u64 v[2:3], v[4:5], 0, s[74:75]
	s_mov_b32 m0, s96
	s_addc_u32 s7, s5, 0
	global_load_lds_dwordx4 v[2:3], off
	s_add_i32 m0, s66, 0x1c000
	v_lshl_add_u64 v[2:3], s[6:7], 0, v[0:1]
	global_load_lds_dwordx4 v[2:3], off
	v_lshl_add_u64 v[2:3], s[6:7], 0, v[174:175]
	s_add_i32 m0, s66, 0x1e000
	s_mov_b64 s[6:7], 0x80080
	global_load_lds_dwordx4 v[2:3], off
	v_lshlrev_b32_e32 v2, 14, v16
	v_and_b32_e32 v2, 0x7fff8000, v2
	v_lshl_add_u32 v2, v15, 11, v2
	v_or_b32_e32 v2, v2, v17
	v_add_lshl_u32 v2, v2, v18, 1
	v_mov_b32_e32 v3, v1
	v_lshl_add_u64 v[176:177], v[2:3], 0, s[6:7]
	v_lshlrev_b32_e32 v2, 14, v10
	v_and_b32_e32 v2, 0x7fff8000, v2
	v_lshl_add_u32 v2, v11, 11, v2
	v_or_b32_e32 v2, v2, v12
	s_waitcnt vmcnt(6)
	v_add_lshl_u32 v2, v2, v14, 1
	s_cmpk_lt_u32 s26, 0x100
	v_lshl_add_u64 v[178:179], v[2:3], 0, s[6:7]
	v_readlane_b32 s6, v255, 34
	s_cselect_b64 s[56:57], -1, 0
	s_mov_b32 s97, 0
	v_cmp_eq_u32_e64 s[36:37], 0, v19
	s_ashr_i32 s26, s8, 31
	v_lshl_or_b32 v206, v19, 2, s27
	v_and_b32_e32 v236, 1, v19
	v_mul_u32_u24_e32 v236, 24, v236
	v_mov_b32_e32 v237, 0
	v_add_u32_e32 v207, 0, v21
	v_readlane_b32 s28, v255, 29
	s_mov_b32 s27, s6
	s_barrier
	v_readlane_b32 s7, v255, 35
	s_branch .LBB0_1196

;     __device__ __forceinline__ void operator()(const f32x4 (&acc)[2][2][4][2], const Unit& u, int wr, int wc, int fr, int fq) const {
;         const int row0 = u.pm * BM + wr * 64 + fr, col0 = u.pn * BM + wc * 32 + 4 * fq;
;         const float* base = (u.pm * BM < TOKP) ? base_p : base_s;
;         const int b = batch_of(u.pm * BM);
;         const float* gp = gate + (size_t)b * (6 * DM) + col0;
;         f32x4 gv[2][2], gg[2][2], gs[2][2];
; #pragma unroll
;         for (int bj = 0; bj < 2; ++bj)
; #pragma unroll
;             for (int n = 0; n < 2; ++n) { gv[bj][n] = LDG(f32x4, gp + bj * HALF + n * 16);
;                 if (NEXT) { gg[bj][n] = LDG(f32x4, gain + col0 + bj * HALF + n * 16); gs[bj][n] = LDG(f32x4, scale + (size_t)b * (6 * DM) + col0 + bj * HALF + n * 16); } }
;         f32x4 bs0[2][2][2];
; #pragma unroll
;         for (int mm = 0; mm < 2; ++mm)
; #pragma unroll
;             for (int bj = 0; bj < 2; ++bj)
; #pragma unroll
;                 for (int n = 0; n < 2; ++n) { const size_t o_ = (size_t)(row0 + mm * 16) * DM + col0 + bj * HALF + n * 16;
;                     if (RES_BF16) { const u32x2 r = LDG(u32x2, xres + o_); bs0[mm][bj][n] = (f32x4){bf_lo(r.x), bf_hi(r.x), bf_lo(r.y), bf_hi(r.y)}; }
;                     else bs0[mm][bj][n] = LDG(f32x4, base + o_); }
;         asm volatile("" ::: "memory");
;         if (NEXT) {
; #pragma unroll
;             for (int bj = 0; bj < 2; ++bj)
; #pragma unroll
;                 for (int n = 0; n < 2; ++n) gg[bj][n] = gg[bj][n] * (gs[bj][n] + 1.0f); }
; #pragma unroll
;         for (int ai = 0; ai < 2; ++ai)
; #pragma unroll
;         for (int mp = 0; mp < 2; ++mp) {
;             f32x4 bs[2][2][2];
; #pragma unroll
;             for (int mm = 0; mm < 2; ++mm)
; #pragma unroll
;                 for (int bj = 0; bj < 2; ++bj)
; #pragma unroll
;                     for (int n = 0; n < 2; ++n) { const size_t o_ = (size_t)(row0 + ai * HALF + (2 * mp + mm) * 16) * DM + col0 + bj * HALF + n * 16;
;                         if (ai == 0 && mp == 0) bs[mm][bj][n] = bs0[mm][bj][n];
;                         else if (RES_BF16) { const u32x2 r = LDG(u32x2, xres + o_); bs[mm][bj][n] = (f32x4){bf_lo(r.x), bf_hi(r.x), bf_lo(r.y), bf_hi(r.y)}; }
;                         else bs[mm][bj][n] = LDG(f32x4, base + o_); }
;             asm volatile("" ::: "memory");
; #pragma unroll
.LBB0_1202:
	s_lshl_b32 s29, s27, 8
	s_add_i32 s4, s29, 0xffffe000
	s_lshr_b32 s4, s4, 12
	s_ashr_i32 s6, s27, 3
	s_add_i32 s7, s4, 4
	s_cmp_lt_i32 s27, 32
	s_cselect_b32 s6, s6, s7
	v_lshl_or_b32 v180, s28, 8, v206
	s_mul_i32 s28, s6, 0xc000
	s_cselect_b32 s5, s45, s49
	s_cselect_b32 s4, s44, s48
	s_mul_hi_i32 s27, s6, 0xc000
	s_add_u32 s6, s79, s28
	v_ashrrev_i32_e32 v181, 31, v180
	s_addc_u32 s7, s83, s27
	v_lshlrev_b64 v[146:147], 2, v[180:181]
	v_lshl_add_u64 v[50:51], s[6:7], 0, v[146:147]
	s_add_u32 s6, s85, s28
	s_addc_u32 s7, s87, s27
	v_lshl_add_u64 v[148:149], s[52:53], 0, v[146:147]
	v_lshl_add_u64 v[150:151], s[6:7], 0, v[146:147]
	global_load_dwordx4 v[62:65], v[50:51], off
	global_load_dwordx4 v[182:185], v[148:149], off
	global_load_dwordx4 v[186:189], v[150:151], off
	global_load_dwordx4 v[58:61], v[50:51], off offset:64
	global_load_dwordx4 v[208:211], v[148:149], off offset:64
	global_load_dwordx4 v[190:193], v[150:151], off offset:64
	global_load_dwordx4 v[54:57], v[50:51], off offset:512
	global_load_dwordx4 v[212:215], v[148:149], off offset:512
	global_load_dwordx4 v[216:219], v[150:151], off offset:512
	s_nop 0
	global_load_dwordx4 v[50:53], v[50:51], off offset:576
	s_nop 0
	global_load_dwordx4 v[220:223], v[148:149], off offset:576
	global_load_dwordx4 v[240:243], v[150:151], off offset:576
	v_add_u32_e32 v200, s29, v204
	v_ashrrev_i32_e32 v201, 31, v200
	v_lshl_add_u64 v[198:199], s[4:5], 0, v[146:147]
	v_lshlrev_b64 v[146:147], 13, v[200:201]
	v_lshl_add_u64 v[146:147], v[198:199], 0, v[146:147]
	global_load_dwordx4 v[244:247], v[146:147], off
	global_load_dwordx4 v[170:173], v[146:147], off offset:64
	global_load_dwordx4 v[166:169], v[146:147], off offset:512
	global_load_dwordx4 v[162:165], v[146:147], off offset:576
	v_or_b32_e32 v202, 16, v200
	v_ashrrev_i32_e32 v203, 31, v202
	v_lshlrev_b64 v[146:147], 13, v[202:203]
	v_lshl_add_u64 v[146:147], v[198:199], 0, v[146:147]
	global_load_dwordx4 v[158:161], v[146:147], off
	global_load_dwordx4 v[154:157], v[146:147], off offset:64
	global_load_dwordx4 v[150:153], v[146:147], off offset:512
	s_nop 0
	global_load_dwordx4 v[146:149], v[146:147], off offset:576
	s_waitcnt vmcnt(0)
	v_pk_add_f32 v[186:187], v[186:187], 1.0 op_sel_hi:[1,0]
	v_pk_add_f32 v[188:189], v[188:189], 1.0 op_sel_hi:[1,0]
	v_pk_mul_f32 v[196:197], v[182:183], v[186:187]
	v_pk_add_f32 v[182:183], v[192:193], 1.0 op_sel_hi:[1,0]
	v_pk_mul_f32 v[194:195], v[184:185], v[188:189]
	v_pk_add_f32 v[184:185], v[190:191], 1.0 op_sel_hi:[1,0]
	v_pk_mul_f32 v[190:191], v[210:211], v[182:183]
	v_pk_add_f32 v[182:183], v[218:219], 1.0 op_sel_hi:[1,0]
	v_pk_mul_f32 v[192:193], v[208:209], v[184:185]
	v_pk_add_f32 v[184:185], v[216:217], 1.0 op_sel_hi:[1,0]
	v_pk_mul_f32 v[186:187], v[214:215], v[182:183]
	v_pk_add_f32 v[182:183], v[242:243], 1.0 op_sel_hi:[1,0]
	v_pk_add_f32 v[208:209], v[240:241], 1.0 op_sel_hi:[1,0]
	v_pk_mul_f32 v[188:189], v[212:213], v[184:185]
	v_pk_mul_f32 v[184:185], v[222:223], v[182:183]
	v_pk_mul_f32 v[182:183], v[220:221], v[208:209]
	v_lshlrev_b64 v[208:209], 11, v[200:201]
	v_lshl_add_u64 v[212:213], v[208:209], 0, v[180:181]
	v_pk_fma_f32 v[210:211], v[144:145], v[64:65], v[246:247]
	v_pk_fma_f32 v[208:209], v[142:143], v[62:63], v[244:245]
	v_mul_f32_e32 v145, v211, v211
	v_mul_f32_e32 v144, v209, v209
	v_lshl_add_u64 v[142:143], v[212:213], 2, s[40:41]
	v_fmac_f32_e32 v144, v208, v208
	v_fmac_f32_e32 v145, v210, v210
	global_store_dwordx4 v[142:143], v[208:211], off
	v_add_f32_e32 v214, v144, v145
	v_pk_mul_f32 v[144:145], v[194:195], v[210:211]
	v_pk_mul_f32 v[208:209], v[196:197], v[208:209]
	v_pk_fma_f32 v[138:139], v[138:139], v[58:59], v[170:171]
	v_cvt_pk_bf16_f32 v248, v208, v209
	v_cvt_pk_bf16_f32 v249, v144, v145
	v_lshl_add_u64 v[144:145], v[212:213], 1, s[42:43]
	v_pk_fma_f32 v[140:141], v[140:141], v[60:61], v[172:173]
	v_mul_f32_e32 v170, v139, v139
	global_store_dwordx4 v[142:143], v[138:141], off offset:64
	v_fmac_f32_e32 v170, v138, v138
	v_mul_f32_e32 v171, v141, v141
	v_pk_mul_f32 v[138:139], v[192:193], v[138:139]
	v_pk_fma_f32 v[134:135], v[134:135], v[54:55], v[166:167]
	v_cvt_pk_bf16_f32 v250, v138, v139
	v_fmac_f32_e32 v171, v140, v140
	v_pk_mul_f32 v[140:141], v[190:191], v[140:141]
	v_pk_fma_f32 v[136:137], v[136:137], v[56:57], v[168:169]
	v_cvt_pk_bf16_f32 v251, v140, v141
	v_lshl_add_u64 v[252:253], v[236:237], 0, v[144:145]
	s_nop 0
	v_permlane16_swap_b32_e32 v248, v250
	v_permlane16_swap_b32_e32 v249, v251
	global_store_dwordx4 v[252:253], v[248:251], off
	s_nop 1
	v_mul_f32_e32 v138, v135, v135
	global_store_dwordx4 v[142:143], v[134:137], off offset:512
	v_fmac_f32_e32 v138, v134, v134
	v_mul_f32_e32 v139, v137, v137
	v_pk_mul_f32 v[134:135], v[188:189], v[134:135]
	v_fmac_f32_e32 v139, v136, v136
	v_pk_mul_f32 v[136:137], v[186:187], v[136:137]
	v_cvt_pk_bf16_f32 v248, v134, v135
	v_pk_fma_f32 v[132:133], v[132:133], v[52:53], v[164:165]
	v_cvt_pk_bf16_f32 v249, v136, v137
	v_pk_fma_f32 v[130:131], v[130:131], v[50:51], v[162:163]
	v_add_f32_e32 v170, v170, v171
	v_mul_f32_e32 v134, v131, v131
	v_mul_f32_e32 v135, v133, v133
	v_add_f32_e32 v170, v214, v170
	v_add_f32_e32 v138, v138, v139
	v_fmac_f32_e32 v134, v130, v130
	v_fmac_f32_e32 v135, v132, v132
	v_add_f32_e32 v138, v170, v138
	global_store_dwordx4 v[142:143], v[130:133], off offset:576
	v_add_f32_e32 v134, v134, v135
	v_add_f32_e32 v134, v138, v134
	v_pk_mul_f32 v[130:131], v[182:183], v[130:131]
	v_pk_mul_f32 v[132:133], v[184:185], v[132:133]
	v_cvt_pk_bf16_f32 v250, v130, v131
	s_nop 0
	v_cvt_pk_bf16_f32 v251, v132, v133
	v_lshl_add_u64 v[252:253], v[236:237], 0, v[144:145]
	s_nop 0
	v_permlane16_swap_b32_e32 v248, v250
	v_permlane16_swap_b32_e32 v249, v251
	global_store_dwordx4 v[252:253], v[248:251], off offset:256
	s_nop 1
	ds_swizzle_b32 v130, v134 offset:swizzle(SWAP,16)
	s_waitcnt lgkmcnt(0)
	v_add_f32_e32 v130, v134, v130
	v_mov_b32_e32 v131, v130
	s_nop 1
	v_permlane32_swap_b32_e32 v130, v131
	v_lshl_add_u64 v[134:135], v[200:201], 2, s[54:55]
	s_and_saveexec_b64 s[4:5], s[36:37]
	s_cbranch_execz .LBB0_1204
	v_add_f32_e32 v130, v130, v131
	global_atomic_add_f32 v[134:135], v130, off
; __device__ __forceinline__ unsigned cvt_pk_bf16(float lo, float hi) { unsigned r; asm volatile("v_cvt_pk_bf16_f32 %0, %1, %2" : "=v"(r) : "v"(lo), "v"(hi)); return r; }
; __device__ __forceinline__ float bf_lo(unsigned w) { return __uint_as_float(w << 16); }
; __device__ __forceinline__ float bf_hi(unsigned w) { return __uint_as_float(w & 0xffff0000u); }
; template <int O> __device__ __forceinline__ float swz_xor(float v) { return __int_as_float(__builtin_amdgcn_ds_swizzle(__float_as_int(v), (O << 10) | 0x1F)); }
;     __device__ __forceinline__ void operator()(const f32x4 (&acc)[2][2][4][2], const Unit& u, int wr, int wc, int fr, int fq) const {
;     ...
;                     for (int n = 0; n < 2; ++n) { const size_t o_ = (size_t)(row0 + ai * HALF + (2 * mp + mm) * 16) * DM + col0 + bj * HALF + n * 16;
;                         if (ai == 0 && mp == 0) bs[mm][bj][n] = bs0[mm][bj][n];
;                         else if (RES_BF16) { const u32x2 r = LDG(u32x2, xres + o_); bs[mm][bj][n] = (f32x4){bf_lo(r.x), bf_hi(r.x), bf_lo(r.y), bf_hi(r.y)}; }
;                         else bs[mm][bj][n] = LDG(f32x4, base + o_); }
;             asm volatile("" ::: "memory");
; #pragma unroll
;             for (int mm = 0; mm < 2; ++mm) { const int m = 2 * mp + mm; const int row = row0 + ai * HALF + m * 16; const size_t off = (size_t)row * DM + col0; float ss = 0.f;
; #pragma unroll
;                 for (int bj = 0; bj < 2; ++bj)
; #pragma unroll
;                     for (int n = 0; n < 2; ++n) { const f32x4 xn = bs[mm][bj][n] + gv[bj][n] * acc[ai][bj][m][n];
;                         if (RES_BF16) { u32x2 w_; w_.x = cvt_pk_bf16(xn[0], xn[1]); w_.y = cvt_pk_bf16(xn[2], xn[3]); STG(u32x2, xres + off + bj * HALF + n * 16) = w_; }
;                         else STG(f32x4, out + off + bj * HALF + n * 16) = xn;
;                         if (NEXT) { ss += (xn[0] * xn[0] + xn[1] * xn[1]) + (xn[2] * xn[2] + xn[3] * xn[3]); const f32x4 y = xn * gg[bj][n];
;                             u32x2 w; w.x = cvt_pk_bf16(y[0], y[1]); w.y = cvt_pk_bf16(y[2], y[3]); STG(u32x2, xg + off + bj * HALF + n * 16) = w; } }
;                 if (NEXT) { ss += swz_xor<16>(ss); auto rr = __builtin_amdgcn_permlane32_swap(__float_as_uint(ss), __float_as_uint(ss), false, false); ss = __uint_as_float(rr[0]) + __uint_as_float(rr[1]);
;                     if (fq == 0) atomicAdd(ssq + row, ss); } }
.LBB0_1204:
	s_or_b64 exec, exec, s[4:5]
	v_lshlrev_b64 v[130:131], 11, v[202:203]
	v_lshl_add_u64 v[130:131], v[130:131], 0, v[180:181]
	v_pk_fma_f32 v[128:129], v[128:129], v[64:65], v[160:161]
	v_pk_fma_f32 v[126:127], v[126:127], v[62:63], v[158:159]
	v_lshl_add_u64 v[132:133], v[130:131], 2, s[40:41]
	v_mul_f32_e32 v136, v127, v127
	v_mul_f32_e32 v137, v129, v129
	global_store_dwordx4 v[132:133], v[126:129], off
	v_fmac_f32_e32 v136, v126, v126
	v_fmac_f32_e32 v137, v128, v128
	v_pk_mul_f32 v[128:129], v[194:195], v[128:129]
	v_pk_mul_f32 v[126:127], v[196:197], v[126:127]
	v_pk_fma_f32 v[122:123], v[122:123], v[58:59], v[154:155]
	v_cvt_pk_bf16_f32 v248, v126, v127
	v_cvt_pk_bf16_f32 v249, v128, v129
	v_lshl_add_u64 v[128:129], v[130:131], 1, s[42:43]
	v_pk_fma_f32 v[124:125], v[124:125], v[60:61], v[156:157]
	v_mul_f32_e32 v126, v123, v123
	global_store_dwordx4 v[132:133], v[122:125], off offset:64
	v_fmac_f32_e32 v126, v122, v122
	v_mul_f32_e32 v127, v125, v125
	v_pk_mul_f32 v[122:123], v[192:193], v[122:123]
	v_pk_fma_f32 v[118:119], v[118:119], v[54:55], v[150:151]
	v_cvt_pk_bf16_f32 v250, v122, v123
	v_fmac_f32_e32 v127, v124, v124
	v_pk_mul_f32 v[124:125], v[190:191], v[124:125]
	v_pk_fma_f32 v[120:121], v[120:121], v[56:57], v[152:153]
	v_cvt_pk_bf16_f32 v251, v124, v125
	v_lshl_add_u64 v[252:253], v[236:237], 0, v[128:129]
	s_nop 0
	v_permlane16_swap_b32_e32 v248, v250
	v_permlane16_swap_b32_e32 v249, v251
	global_store_dwordx4 v[252:253], v[248:251], off
	s_nop 1
	v_mul_f32_e32 v122, v119, v119
	global_store_dwordx4 v[132:133], v[118:121], off offset:512
	v_fmac_f32_e32 v122, v118, v118
	v_mul_f32_e32 v123, v121, v121
	v_pk_mul_f32 v[118:119], v[188:189], v[118:119]
	v_fmac_f32_e32 v123, v120, v120
	v_pk_mul_f32 v[120:121], v[186:187], v[120:121]
	v_cvt_pk_bf16_f32 v248, v118, v119
	v_pk_fma_f32 v[116:117], v[116:117], v[52:53], v[148:149]
	v_cvt_pk_bf16_f32 v249, v120, v121
	v_pk_fma_f32 v[114:115], v[114:115], v[50:51], v[146:147]
	v_add_f32_e32 v136, v136, v137
	v_add_f32_e32 v126, v126, v127
	v_mul_f32_e32 v118, v115, v115
	v_mul_f32_e32 v119, v117, v117
	v_add_f32_e32 v126, v136, v126
	v_add_f32_e32 v122, v122, v123
	v_fmac_f32_e32 v118, v114, v114
	v_fmac_f32_e32 v119, v116, v116
	v_add_f32_e32 v122, v126, v122
	v_add_f32_e32 v118, v118, v119
	v_add_f32_e32 v118, v122, v118
	ds_swizzle_b32 v119, v118 offset:swizzle(SWAP,16)
	global_store_dwordx4 v[132:133], v[114:117], off offset:576
	s_nop 1
	v_pk_mul_f32 v[114:115], v[182:183], v[114:115]
	v_pk_mul_f32 v[116:117], v[184:185], v[116:117]
	v_cvt_pk_bf16_f32 v250, v114, v115
	s_nop 0
	v_cvt_pk_bf16_f32 v251, v116, v117
	v_lshl_add_u64 v[252:253], v[236:237], 0, v[128:129]
	s_nop 0
	v_permlane16_swap_b32_e32 v248, v250
	v_permlane16_swap_b32_e32 v249, v251
	global_store_dwordx4 v[252:253], v[248:251], off offset:256
	s_nop 1
	s_waitcnt lgkmcnt(0)
	v_add_f32_e32 v114, v118, v119
	v_mov_b32_e32 v115, v114
	s_nop 1
	v_permlane32_swap_b32_e32 v114, v115
	s_and_saveexec_b64 s[4:5], s[36:37]
	s_cbranch_execz .LBB0_1206
	v_add_f32_e32 v114, v114, v115
	global_atomic_add_f32 v[134:135], v114, off offset:64
.LBB0_1206:
	s_or_b64 exec, exec, s[4:5]
	v_or_b32_e32 v150, 32, v200
	v_ashrrev_i32_e32 v151, 31, v150
	v_lshlrev_b64 v[114:115], 13, v[150:151]
	v_lshl_add_u64 v[114:115], v[198:199], 0, v[114:115]
	global_load_dwordx4 v[138:141], v[114:115], off
	global_load_dwordx4 v[142:145], v[114:115], off offset:64
	global_load_dwordx4 v[146:149], v[114:115], off offset:512
	global_load_dwordx4 v[130:133], v[114:115], off offset:576
	v_or_b32_e32 v136, 48, v200
	v_ashrrev_i32_e32 v137, 31, v136
	v_lshlrev_b64 v[114:115], 13, v[136:137]
	v_lshl_add_u64 v[114:115], v[198:199], 0, v[114:115]
	global_load_dwordx4 v[126:129], v[114:115], off
	global_load_dwordx4 v[122:125], v[114:115], off offset:64
	global_load_dwordx4 v[118:121], v[114:115], off offset:512
	s_nop 0
	global_load_dwordx4 v[114:117], v[114:115], off offset:576
	v_lshlrev_b64 v[150:151], 11, v[150:151]
	v_lshl_add_u64 v[150:151], v[150:151], 0, v[180:181]
	s_waitcnt vmcnt(7)
	v_pk_fma_f32 v[112:113], v[112:113], v[64:65], v[140:141]
	v_pk_fma_f32 v[110:111], v[110:111], v[62:63], v[138:139]
	v_lshl_add_u64 v[138:139], v[150:151], 2, s[40:41]
	v_mul_f32_e32 v140, v111, v111
	v_mul_f32_e32 v141, v113, v113
	global_store_dwordx4 v[138:139], v[110:113], off
	v_fmac_f32_e32 v140, v110, v110
	v_fmac_f32_e32 v141, v112, v112
	v_pk_mul_f32 v[112:113], v[194:195], v[112:113]
	v_pk_mul_f32 v[110:111], v[196:197], v[110:111]
	s_waitcnt vmcnt(7)
	v_pk_fma_f32 v[106:107], v[106:107], v[58:59], v[142:143]
	v_add_f32_e32 v152, v140, v141
	v_cvt_pk_bf16_f32 v248, v110, v111
	v_cvt_pk_bf16_f32 v249, v112, v113
	v_lshl_add_u64 v[110:111], v[150:151], 1, s[42:43]
	v_pk_fma_f32 v[108:109], v[108:109], v[60:61], v[144:145]
	v_mul_f32_e32 v112, v107, v107
	global_store_dwordx4 v[138:139], v[106:109], off offset:64
	v_fmac_f32_e32 v112, v106, v106
	v_mul_f32_e32 v113, v109, v109
	v_pk_mul_f32 v[106:107], v[192:193], v[106:107]
	s_waitcnt vmcnt(7)
	v_pk_fma_f32 v[102:103], v[102:103], v[54:55], v[146:147]
	v_cvt_pk_bf16_f32 v250, v106, v107
	v_fmac_f32_e32 v113, v108, v108
	v_pk_mul_f32 v[108:109], v[190:191], v[108:109]
	v_pk_fma_f32 v[104:105], v[104:105], v[56:57], v[148:149]
	v_cvt_pk_bf16_f32 v251, v108, v109
	v_lshl_add_u64 v[252:253], v[236:237], 0, v[110:111]
	s_nop 0
	v_permlane16_swap_b32_e32 v248, v250
	v_permlane16_swap_b32_e32 v249, v251
	global_store_dwordx4 v[252:253], v[248:251], off
	s_nop 1
	v_mul_f32_e32 v106, v103, v103
	global_store_dwordx4 v[138:139], v[102:105], off offset:512
	v_fmac_f32_e32 v106, v102, v102
	v_mul_f32_e32 v107, v105, v105
	v_pk_mul_f32 v[102:103], v[188:189], v[102:103]
	v_fmac_f32_e32 v107, v104, v104
	v_pk_mul_f32 v[104:105], v[186:187], v[104:105]
	v_cvt_pk_bf16_f32 v248, v102, v103
	s_waitcnt vmcnt(8)
	v_pk_fma_f32 v[100:101], v[100:101], v[52:53], v[132:133]
	v_cvt_pk_bf16_f32 v249, v104, v105
	v_pk_fma_f32 v[98:99], v[98:99], v[50:51], v[130:131]
	v_add_f32_e32 v112, v112, v113
	v_mul_f32_e32 v102, v99, v99
	v_mul_f32_e32 v103, v101, v101
	v_add_f32_e32 v112, v152, v112
	v_add_f32_e32 v106, v106, v107
	v_fmac_f32_e32 v102, v98, v98
	v_fmac_f32_e32 v103, v100, v100
	v_add_f32_e32 v106, v112, v106
	global_store_dwordx4 v[138:139], v[98:101], off offset:576
	v_add_f32_e32 v102, v102, v103
	v_add_f32_e32 v102, v106, v102
	v_pk_mul_f32 v[98:99], v[182:183], v[98:99]
	v_pk_mul_f32 v[100:101], v[184:185], v[100:101]
	v_cvt_pk_bf16_f32 v250, v98, v99
	s_nop 0
	v_cvt_pk_bf16_f32 v251, v100, v101
	v_lshl_add_u64 v[252:253], v[236:237], 0, v[110:111]
	s_nop 0
	v_permlane16_swap_b32_e32 v248, v250
	v_permlane16_swap_b32_e32 v249, v251
	global_store_dwordx4 v[252:253], v[248:251], off offset:256
	s_nop 1
	ds_swizzle_b32 v98, v102 offset:swizzle(SWAP,16)
	s_waitcnt lgkmcnt(0)
	v_add_f32_e32 v98, v102, v98
	v_mov_b32_e32 v99, v98
	s_nop 1
	v_permlane32_swap_b32_e32 v98, v99
	s_and_saveexec_b64 s[4:5], s[36:37]
	s_mov_b32 s94, 0x2c000
	s_cbranch_execz .LBB0_1208
; __device__ __forceinline__ unsigned cvt_pk_bf16(float lo, float hi) { unsigned r; asm volatile("v_cvt_pk_bf16_f32 %0, %1, %2" : "=v"(r) : "v"(lo), "v"(hi)); return r; }
; __device__ __forceinline__ float bf_lo(unsigned w) { return __uint_as_float(w << 16); }
; __device__ __forceinline__ float bf_hi(unsigned w) { return __uint_as_float(w & 0xffff0000u); }
; template <int O> __device__ __forceinline__ float swz_xor(float v) { return __int_as_float(__builtin_amdgcn_ds_swizzle(__float_as_int(v), (O << 10) | 0x1F)); }
;     __device__ __forceinline__ void operator()(const f32x4 (&acc)[2][2][4][2], const Unit& u, int wr, int wc, int fr, int fq) const {
;     ...
;                     for (int n = 0; n < 2; ++n) { const size_t o_ = (size_t)(row0 + ai * HALF + (2 * mp + mm) * 16) * DM + col0 + bj * HALF + n * 16;
;                         if (ai == 0 && mp == 0) bs[mm][bj][n] = bs0[mm][bj][n];
;                         else if (RES_BF16) { const u32x2 r = LDG(u32x2, xres + o_); bs[mm][bj][n] = (f32x4){bf_lo(r.x), bf_hi(r.x), bf_lo(r.y), bf_hi(r.y)}; }
;                         else bs[mm][bj][n] = LDG(f32x4, base + o_); }
;             asm volatile("" ::: "memory");
; #pragma unroll
;             for (int mm = 0; mm < 2; ++mm) { const int m = 2 * mp + mm; const int row = row0 + ai * HALF + m * 16; const size_t off = (size_t)row * DM + col0; float ss = 0.f;
; #pragma unroll
;                 for (int bj = 0; bj < 2; ++bj)
; #pragma unroll
;                     for (int n = 0; n < 2; ++n) { const f32x4 xn = bs[mm][bj][n] + gv[bj][n] * acc[ai][bj][m][n];
;                         if (RES_BF16) { u32x2 w_; w_.x = cvt_pk_bf16(xn[0], xn[1]); w_.y = cvt_pk_bf16(xn[2], xn[3]); STG(u32x2, xres + off + bj * HALF + n * 16) = w_; }
;                         else STG(f32x4, out + off + bj * HALF + n * 16) = xn;
;                         if (NEXT) { ss += (xn[0] * xn[0] + xn[1] * xn[1]) + (xn[2] * xn[2] + xn[3] * xn[3]); const f32x4 y = xn * gg[bj][n];
;                             u32x2 w; w.x = cvt_pk_bf16(y[0], y[1]); w.y = cvt_pk_bf16(y[2], y[3]); STG(u32x2, xg + off + bj * HALF + n * 16) = w; } }
;                 if (NEXT) { ss += swz_xor<16>(ss); auto rr = __builtin_amdgcn_permlane32_swap(__float_as_uint(ss), __float_as_uint(ss), false, false); ss = __uint_as_float(rr[0]) + __uint_as_float(rr[1]);
;                     if (fq == 0) atomicAdd(ssq + row, ss); } }
	v_add_f32_e32 v98, v98, v99
	global_atomic_add_f32 v[134:135], v98, off offset:128
.LBB0_1208:
	s_or_b64 exec, exec, s[4:5]
	v_lshlrev_b64 v[98:99], 11, v[136:137]
	v_lshl_add_u64 v[98:99], v[98:99], 0, v[180:181]
	s_waitcnt vmcnt(9)
	v_pk_fma_f32 v[96:97], v[96:97], v[64:65], v[128:129]
	v_pk_fma_f32 v[94:95], v[94:95], v[62:63], v[126:127]
	v_lshl_add_u64 v[100:101], v[98:99], 2, s[40:41]
	v_mul_f32_e32 v102, v95, v95
	v_mul_f32_e32 v103, v97, v97
	global_store_dwordx4 v[100:101], v[94:97], off
	v_fmac_f32_e32 v102, v94, v94
	v_fmac_f32_e32 v103, v96, v96
	v_pk_mul_f32 v[96:97], v[194:195], v[96:97]
	v_pk_mul_f32 v[94:95], v[196:197], v[94:95]
	s_waitcnt vmcnt(9)
	v_pk_fma_f32 v[90:91], v[90:91], v[58:59], v[122:123]
	v_cvt_pk_bf16_f32 v248, v94, v95
	v_cvt_pk_bf16_f32 v249, v96, v97
	v_lshl_add_u64 v[96:97], v[98:99], 1, s[42:43]
	v_pk_fma_f32 v[92:93], v[92:93], v[60:61], v[124:125]
	v_mul_f32_e32 v94, v91, v91
	global_store_dwordx4 v[100:101], v[90:93], off offset:64
	v_fmac_f32_e32 v94, v90, v90
	v_mul_f32_e32 v95, v93, v93
	v_pk_mul_f32 v[90:91], v[192:193], v[90:91]
	s_waitcnt vmcnt(9)
	v_pk_fma_f32 v[86:87], v[86:87], v[54:55], v[118:119]
	v_cvt_pk_bf16_f32 v250, v90, v91
	v_fmac_f32_e32 v95, v92, v92
	v_pk_mul_f32 v[92:93], v[190:191], v[92:93]
	v_pk_fma_f32 v[88:89], v[88:89], v[56:57], v[120:121]
	v_cvt_pk_bf16_f32 v251, v92, v93
	v_lshl_add_u64 v[252:253], v[236:237], 0, v[96:97]
	s_nop 0
	v_permlane16_swap_b32_e32 v248, v250
	v_permlane16_swap_b32_e32 v249, v251
	global_store_dwordx4 v[252:253], v[248:251], off
	s_nop 1
	v_mul_f32_e32 v90, v87, v87
	global_store_dwordx4 v[100:101], v[86:89], off offset:512
	v_fmac_f32_e32 v90, v86, v86
	v_mul_f32_e32 v91, v89, v89
	v_pk_mul_f32 v[86:87], v[188:189], v[86:87]
	v_fmac_f32_e32 v91, v88, v88
	v_pk_mul_f32 v[88:89], v[186:187], v[88:89]
	v_cvt_pk_bf16_f32 v248, v86, v87
	s_waitcnt vmcnt(10)
	v_pk_fma_f32 v[84:85], v[84:85], v[52:53], v[116:117]
	v_cvt_pk_bf16_f32 v249, v88, v89
	v_pk_fma_f32 v[82:83], v[82:83], v[50:51], v[114:115]
	v_add_f32_e32 v102, v102, v103
	v_add_f32_e32 v94, v94, v95
	v_mul_f32_e32 v86, v83, v83
	v_mul_f32_e32 v87, v85, v85
	v_add_f32_e32 v94, v102, v94
	v_add_f32_e32 v90, v90, v91
	v_fmac_f32_e32 v86, v82, v82
	v_fmac_f32_e32 v87, v84, v84
	v_add_f32_e32 v90, v94, v90
	v_add_f32_e32 v86, v86, v87
	v_add_f32_e32 v86, v90, v86
	ds_swizzle_b32 v87, v86 offset:swizzle(SWAP,16)
	global_store_dwordx4 v[100:101], v[82:85], off offset:576
	s_nop 1
	v_pk_mul_f32 v[82:83], v[182:183], v[82:83]
	v_pk_mul_f32 v[84:85], v[184:185], v[84:85]
	v_cvt_pk_bf16_f32 v250, v82, v83
	s_nop 0
	v_cvt_pk_bf16_f32 v251, v84, v85
	v_lshl_add_u64 v[252:253], v[236:237], 0, v[96:97]
	s_nop 0
	v_permlane16_swap_b32_e32 v248, v250
	v_permlane16_swap_b32_e32 v249, v251
	global_store_dwordx4 v[252:253], v[248:251], off offset:256
	s_nop 1
	s_waitcnt lgkmcnt(0)
	v_add_f32_e32 v82, v86, v87
	v_mov_b32_e32 v83, v82
	s_nop 1
	v_permlane32_swap_b32_e32 v82, v83
	s_and_saveexec_b64 s[4:5], s[36:37]
	s_cbranch_execz .LBB0_1210
	v_add_f32_e32 v82, v82, v83
	global_atomic_add_f32 v[134:135], v82, off offset:192
.LBB0_1210:
	s_or_b64 exec, exec, s[4:5]
	v_add_u32_e32 v116, 0x80, v200
	v_ashrrev_i32_e32 v117, 31, v116
	v_lshlrev_b64 v[82:83], 13, v[116:117]
	v_lshl_add_u64 v[82:83], v[198:199], 0, v[82:83]
	global_load_dwordx4 v[104:107], v[82:83], off
	global_load_dwordx4 v[108:111], v[82:83], off offset:64
	global_load_dwordx4 v[112:115], v[82:83], off offset:512
	global_load_dwordx4 v[98:101], v[82:83], off offset:576
	v_add_u32_e32 v102, 0x90, v200
	v_ashrrev_i32_e32 v103, 31, v102
	v_lshlrev_b64 v[82:83], 13, v[102:103]
	v_lshl_add_u64 v[82:83], v[198:199], 0, v[82:83]
	global_load_dwordx4 v[94:97], v[82:83], off
	global_load_dwordx4 v[90:93], v[82:83], off offset:64
	global_load_dwordx4 v[86:89], v[82:83], off offset:512
	s_nop 0
	global_load_dwordx4 v[82:85], v[82:83], off offset:576
	v_lshlrev_b64 v[116:117], 11, v[116:117]
	v_lshl_add_u64 v[116:117], v[116:117], 0, v[180:181]
	s_waitcnt vmcnt(7)
	v_pk_fma_f32 v[80:81], v[80:81], v[64:65], v[106:107]
	v_pk_fma_f32 v[78:79], v[78:79], v[62:63], v[104:105]
	v_lshl_add_u64 v[104:105], v[116:117], 2, s[40:41]
	v_mul_f32_e32 v106, v79, v79
	v_mul_f32_e32 v107, v81, v81
	global_store_dwordx4 v[104:105], v[78:81], off
	v_fmac_f32_e32 v106, v78, v78
	v_fmac_f32_e32 v107, v80, v80
	v_pk_mul_f32 v[80:81], v[194:195], v[80:81]
	v_pk_mul_f32 v[78:79], v[196:197], v[78:79]
	s_waitcnt vmcnt(7)
	v_pk_fma_f32 v[74:75], v[74:75], v[58:59], v[108:109]
	v_add_f32_e32 v118, v106, v107
	v_cvt_pk_bf16_f32 v248, v78, v79
	v_cvt_pk_bf16_f32 v249, v80, v81
	v_lshl_add_u64 v[78:79], v[116:117], 1, s[42:43]
	v_pk_fma_f32 v[76:77], v[76:77], v[60:61], v[110:111]
	v_mul_f32_e32 v80, v75, v75
	global_store_dwordx4 v[104:105], v[74:77], off offset:64
	v_fmac_f32_e32 v80, v74, v74
	v_mul_f32_e32 v81, v77, v77
	v_pk_mul_f32 v[74:75], v[192:193], v[74:75]
	s_waitcnt vmcnt(7)
	v_pk_fma_f32 v[70:71], v[70:71], v[54:55], v[112:113]
	v_cvt_pk_bf16_f32 v250, v74, v75
	v_fmac_f32_e32 v81, v76, v76
	v_pk_mul_f32 v[76:77], v[190:191], v[76:77]
	v_pk_fma_f32 v[72:73], v[72:73], v[56:57], v[114:115]
	v_cvt_pk_bf16_f32 v251, v76, v77
	v_lshl_add_u64 v[252:253], v[236:237], 0, v[78:79]
	s_nop 0
	v_permlane16_swap_b32_e32 v248, v250
	v_permlane16_swap_b32_e32 v249, v251
	global_store_dwordx4 v[252:253], v[248:251], off
	s_nop 1
	v_mul_f32_e32 v74, v71, v71
	global_store_dwordx4 v[104:105], v[70:73], off offset:512
	v_fmac_f32_e32 v74, v70, v70
	v_mul_f32_e32 v75, v73, v73
	v_pk_mul_f32 v[70:71], v[188:189], v[70:71]
	v_fmac_f32_e32 v75, v72, v72
	v_pk_mul_f32 v[72:73], v[186:187], v[72:73]
	v_cvt_pk_bf16_f32 v248, v70, v71
	s_waitcnt vmcnt(8)
	v_pk_fma_f32 v[68:69], v[68:69], v[52:53], v[100:101]
	v_cvt_pk_bf16_f32 v249, v72, v73
	v_pk_fma_f32 v[66:67], v[66:67], v[50:51], v[98:99]
	v_add_f32_e32 v80, v80, v81
	v_mul_f32_e32 v70, v67, v67
	v_mul_f32_e32 v71, v69, v69
	v_add_f32_e32 v80, v118, v80
	v_add_f32_e32 v74, v74, v75
	v_fmac_f32_e32 v70, v66, v66
	v_fmac_f32_e32 v71, v68, v68
	v_add_f32_e32 v74, v80, v74
	global_store_dwordx4 v[104:105], v[66:69], off offset:576
	v_add_f32_e32 v70, v70, v71
	v_add_f32_e32 v70, v74, v70
	v_pk_mul_f32 v[66:67], v[182:183], v[66:67]
	v_pk_mul_f32 v[68:69], v[184:185], v[68:69]
	v_cvt_pk_bf16_f32 v250, v66, v67
	s_nop 0
	v_cvt_pk_bf16_f32 v251, v68, v69
	v_lshl_add_u64 v[252:253], v[236:237], 0, v[78:79]
	s_nop 0
	v_permlane16_swap_b32_e32 v248, v250
	v_permlane16_swap_b32_e32 v249, v251
	global_store_dwordx4 v[252:253], v[248:251], off offset:256
	s_nop 1
	ds_swizzle_b32 v66, v70 offset:swizzle(SWAP,16)
	s_waitcnt lgkmcnt(0)
	v_add_f32_e32 v66, v70, v66
	v_mov_b32_e32 v67, v66
	s_nop 1
	v_permlane32_swap_b32_e32 v66, v67
	s_and_saveexec_b64 s[4:5], s[36:37]
	s_cbranch_execz .LBB0_1212
	v_add_f32_e32 v66, v66, v67
	global_atomic_add_f32 v[134:135], v66, off offset:512
; __device__ __forceinline__ unsigned cvt_pk_bf16(float lo, float hi) { unsigned r; asm volatile("v_cvt_pk_bf16_f32 %0, %1, %2" : "=v"(r) : "v"(lo), "v"(hi)); return r; }
; template <int O> __device__ __forceinline__ float swz_xor(float v) { return __int_as_float(__builtin_amdgcn_ds_swizzle(__float_as_int(v), (O << 10) | 0x1F)); }
;     __device__ __forceinline__ void operator()(const f32x4 (&acc)[2][2][4][2], const Unit& u, int wr, int wc, int fr, int fq) const {
;     ...
;             for (int mm = 0; mm < 2; ++mm) { const int m = 2 * mp + mm; const int row = row0 + ai * HALF + m * 16; const size_t off = (size_t)row * DM + col0; float ss = 0.f;
; #pragma unroll
;                 for (int bj = 0; bj < 2; ++bj)
; #pragma unroll
;                     for (int n = 0; n < 2; ++n) { const f32x4 xn = bs[mm][bj][n] + gv[bj][n] * acc[ai][bj][m][n];
;                         if (RES_BF16) { u32x2 w_; w_.x = cvt_pk_bf16(xn[0], xn[1]); w_.y = cvt_pk_bf16(xn[2], xn[3]); STG(u32x2, xres + off + bj * HALF + n * 16) = w_; }
;                         else STG(f32x4, out + off + bj * HALF + n * 16) = xn;
;                         if (NEXT) { ss += (xn[0] * xn[0] + xn[1] * xn[1]) + (xn[2] * xn[2] + xn[3] * xn[3]); const f32x4 y = xn * gg[bj][n];
;                             u32x2 w; w.x = cvt_pk_bf16(y[0], y[1]); w.y = cvt_pk_bf16(y[2], y[3]); STG(u32x2, xg + off + bj * HALF + n * 16) = w; } }
;                 if (NEXT) { ss += swz_xor<16>(ss); auto rr = __builtin_amdgcn_permlane32_swap(__float_as_uint(ss), __float_as_uint(ss), false, false); ss = __uint_as_float(rr[0]) + __uint_as_float(rr[1]);
;                     if (fq == 0) atomicAdd(ssq + row, ss); } }
.LBB0_1212:
	s_or_b64 exec, exec, s[4:5]
	v_lshlrev_b64 v[66:67], 11, v[102:103]
	v_lshl_add_u64 v[66:67], v[66:67], 0, v[180:181]
	s_waitcnt vmcnt(9)
	v_pk_fma_f32 v[48:49], v[48:49], v[64:65], v[96:97]
	v_pk_fma_f32 v[46:47], v[46:47], v[62:63], v[94:95]
	v_lshl_add_u64 v[68:69], v[66:67], 2, s[40:41]
	v_mul_f32_e32 v70, v47, v47
	v_mul_f32_e32 v71, v49, v49
	global_store_dwordx4 v[68:69], v[46:49], off
	v_fmac_f32_e32 v70, v46, v46
	v_fmac_f32_e32 v71, v48, v48
	v_pk_mul_f32 v[48:49], v[194:195], v[48:49]
	v_pk_mul_f32 v[46:47], v[196:197], v[46:47]
	s_waitcnt vmcnt(9)
	v_pk_fma_f32 v[42:43], v[42:43], v[58:59], v[90:91]
	v_cvt_pk_bf16_f32 v248, v46, v47
	v_cvt_pk_bf16_f32 v249, v48, v49
	v_lshl_add_u64 v[48:49], v[66:67], 1, s[42:43]
	v_pk_fma_f32 v[44:45], v[44:45], v[60:61], v[92:93]
	v_mul_f32_e32 v46, v43, v43
	global_store_dwordx4 v[68:69], v[42:45], off offset:64
	v_fmac_f32_e32 v46, v42, v42
	v_mul_f32_e32 v47, v45, v45
	v_pk_mul_f32 v[42:43], v[192:193], v[42:43]
	s_waitcnt vmcnt(9)
	v_pk_fma_f32 v[38:39], v[38:39], v[54:55], v[86:87]
	v_cvt_pk_bf16_f32 v250, v42, v43
	v_fmac_f32_e32 v47, v44, v44
	v_pk_mul_f32 v[44:45], v[190:191], v[44:45]
	v_pk_fma_f32 v[40:41], v[40:41], v[56:57], v[88:89]
	v_cvt_pk_bf16_f32 v251, v44, v45
	v_lshl_add_u64 v[252:253], v[236:237], 0, v[48:49]
	s_nop 0
	v_permlane16_swap_b32_e32 v248, v250
	v_permlane16_swap_b32_e32 v249, v251
	global_store_dwordx4 v[252:253], v[248:251], off
	s_nop 1
	v_mul_f32_e32 v42, v39, v39
	global_store_dwordx4 v[68:69], v[38:41], off offset:512
	v_fmac_f32_e32 v42, v38, v38
	v_mul_f32_e32 v43, v41, v41
	v_pk_mul_f32 v[38:39], v[188:189], v[38:39]
	v_fmac_f32_e32 v43, v40, v40
	v_pk_mul_f32 v[40:41], v[186:187], v[40:41]
	v_cvt_pk_bf16_f32 v248, v38, v39
	s_waitcnt vmcnt(10)
	v_pk_fma_f32 v[36:37], v[36:37], v[52:53], v[84:85]
	v_cvt_pk_bf16_f32 v249, v40, v41
	v_pk_fma_f32 v[34:35], v[34:35], v[50:51], v[82:83]
	v_add_f32_e32 v70, v70, v71
	v_add_f32_e32 v46, v46, v47
	v_mul_f32_e32 v38, v35, v35
	v_mul_f32_e32 v39, v37, v37
	v_add_f32_e32 v46, v70, v46
	v_add_f32_e32 v42, v42, v43
	v_fmac_f32_e32 v38, v34, v34
	v_fmac_f32_e32 v39, v36, v36
	v_add_f32_e32 v42, v46, v42
	v_add_f32_e32 v38, v38, v39
	v_add_f32_e32 v38, v42, v38
	ds_swizzle_b32 v39, v38 offset:swizzle(SWAP,16)
	global_store_dwordx4 v[68:69], v[34:37], off offset:576
	s_nop 1
	v_pk_mul_f32 v[34:35], v[182:183], v[34:35]
	v_pk_mul_f32 v[36:37], v[184:185], v[36:37]
	v_cvt_pk_bf16_f32 v250, v34, v35
	s_nop 0
	v_cvt_pk_bf16_f32 v251, v36, v37
	v_lshl_add_u64 v[252:253], v[236:237], 0, v[48:49]
	s_nop 0
	v_permlane16_swap_b32_e32 v248, v250
	v_permlane16_swap_b32_e32 v249, v251
	global_store_dwordx4 v[252:253], v[248:251], off offset:256
	s_nop 1
	s_waitcnt lgkmcnt(0)
	v_add_f32_e32 v34, v38, v39
	v_mov_b32_e32 v35, v34
	s_nop 1
	v_permlane32_swap_b32_e32 v34, v35
	s_and_saveexec_b64 s[4:5], s[36:37]
	s_cbranch_execz .LBB0_1214
	v_add_f32_e32 v34, v34, v35
	global_atomic_add_f32 v[134:135], v34, off offset:576
; __device__ __forceinline__ unsigned cvt_pk_bf16(float lo, float hi) { unsigned r; asm volatile("v_cvt_pk_bf16_f32 %0, %1, %2" : "=v"(r) : "v"(lo), "v"(hi)); return r; }
; __device__ __forceinline__ float bf_lo(unsigned w) { return __uint_as_float(w << 16); }
; __device__ __forceinline__ float bf_hi(unsigned w) { return __uint_as_float(w & 0xffff0000u); }
; template <int O> __device__ __forceinline__ float swz_xor(float v) { return __int_as_float(__builtin_amdgcn_ds_swizzle(__float_as_int(v), (O << 10) | 0x1F)); }
;     __device__ __forceinline__ void operator()(const f32x4 (&acc)[2][2][4][2], const Unit& u, int wr, int wc, int fr, int fq) const {
;     ...
;                     for (int n = 0; n < 2; ++n) { const size_t o_ = (size_t)(row0 + ai * HALF + (2 * mp + mm) * 16) * DM + col0 + bj * HALF + n * 16;
;                         if (ai == 0 && mp == 0) bs[mm][bj][n] = bs0[mm][bj][n];
;                         else if (RES_BF16) { const u32x2 r = LDG(u32x2, xres + o_); bs[mm][bj][n] = (f32x4){bf_lo(r.x), bf_hi(r.x), bf_lo(r.y), bf_hi(r.y)}; }
;                         else bs[mm][bj][n] = LDG(f32x4, base + o_); }
;             asm volatile("" ::: "memory");
; #pragma unroll
;             for (int mm = 0; mm < 2; ++mm) { const int m = 2 * mp + mm; const int row = row0 + ai * HALF + m * 16; const size_t off = (size_t)row * DM + col0; float ss = 0.f;
; #pragma unroll
;                 for (int bj = 0; bj < 2; ++bj)
; #pragma unroll
;                     for (int n = 0; n < 2; ++n) { const f32x4 xn = bs[mm][bj][n] + gv[bj][n] * acc[ai][bj][m][n];
;                         if (RES_BF16) { u32x2 w_; w_.x = cvt_pk_bf16(xn[0], xn[1]); w_.y = cvt_pk_bf16(xn[2], xn[3]); STG(u32x2, xres + off + bj * HALF + n * 16) = w_; }
;                         else STG(f32x4, out + off + bj * HALF + n * 16) = xn;
;                         if (NEXT) { ss += (xn[0] * xn[0] + xn[1] * xn[1]) + (xn[2] * xn[2] + xn[3] * xn[3]); const f32x4 y = xn * gg[bj][n];
;                             u32x2 w; w.x = cvt_pk_bf16(y[0], y[1]); w.y = cvt_pk_bf16(y[2], y[3]); STG(u32x2, xg + off + bj * HALF + n * 16) = w; } }
;                 if (NEXT) { ss += swz_xor<16>(ss); auto rr = __builtin_amdgcn_permlane32_swap(__float_as_uint(ss), __float_as_uint(ss), false, false); ss = __uint_as_float(rr[0]) + __uint_as_float(rr[1]);
;                     if (fq == 0) atomicAdd(ssq + row, ss); } }
.LBB0_1214:
	s_or_b64 exec, exec, s[4:5]
	v_add_u32_e32 v84, 0xa0, v200
	v_ashrrev_i32_e32 v85, 31, v84
	v_lshlrev_b64 v[34:35], 13, v[84:85]
	v_lshl_add_u64 v[34:35], v[198:199], 0, v[34:35]
	global_load_dwordx4 v[72:75], v[34:35], off
	global_load_dwordx4 v[76:79], v[34:35], off offset:64
	global_load_dwordx4 v[80:83], v[34:35], off offset:512
	global_load_dwordx4 v[66:69], v[34:35], off offset:576
	v_add_u32_e32 v70, 0xb0, v200
	v_ashrrev_i32_e32 v71, 31, v70
	v_lshlrev_b64 v[34:35], 13, v[70:71]
	v_lshl_add_u64 v[34:35], v[198:199], 0, v[34:35]
	global_load_dwordx4 v[46:49], v[34:35], off
	global_load_dwordx4 v[42:45], v[34:35], off offset:64
	global_load_dwordx4 v[38:41], v[34:35], off offset:512
	s_nop 0
	global_load_dwordx4 v[34:37], v[34:35], off offset:576
	v_lshlrev_b64 v[84:85], 11, v[84:85]
	v_lshl_add_u64 v[84:85], v[84:85], 0, v[180:181]
	s_waitcnt vmcnt(7)
	v_pk_fma_f32 v[32:33], v[32:33], v[64:65], v[74:75]
	v_pk_fma_f32 v[30:31], v[30:31], v[62:63], v[72:73]
	v_lshl_add_u64 v[72:73], v[84:85], 2, s[40:41]
	v_mul_f32_e32 v74, v31, v31
	v_mul_f32_e32 v75, v33, v33
	global_store_dwordx4 v[72:73], v[30:33], off
	v_fmac_f32_e32 v74, v30, v30
	v_fmac_f32_e32 v75, v32, v32
	v_pk_mul_f32 v[32:33], v[194:195], v[32:33]
	v_pk_mul_f32 v[30:31], v[196:197], v[30:31]
	s_waitcnt vmcnt(7)
	v_pk_fma_f32 v[26:27], v[26:27], v[58:59], v[76:77]
	v_add_f32_e32 v86, v74, v75
	v_cvt_pk_bf16_f32 v248, v30, v31
	v_cvt_pk_bf16_f32 v249, v32, v33
	v_lshl_add_u64 v[30:31], v[84:85], 1, s[42:43]
	v_pk_fma_f32 v[28:29], v[28:29], v[60:61], v[78:79]
	v_mul_f32_e32 v32, v27, v27
	global_store_dwordx4 v[72:73], v[26:29], off offset:64
	v_fmac_f32_e32 v32, v26, v26
	v_mul_f32_e32 v33, v29, v29
	v_pk_mul_f32 v[26:27], v[192:193], v[26:27]
	s_waitcnt vmcnt(7)
	v_pk_fma_f32 v[22:23], v[22:23], v[54:55], v[80:81]
	v_cvt_pk_bf16_f32 v250, v26, v27
	v_fmac_f32_e32 v33, v28, v28
	v_pk_mul_f32 v[28:29], v[190:191], v[28:29]
	v_pk_fma_f32 v[24:25], v[24:25], v[56:57], v[82:83]
	v_cvt_pk_bf16_f32 v251, v28, v29
	v_lshl_add_u64 v[252:253], v[236:237], 0, v[30:31]
	s_nop 0
	v_permlane16_swap_b32_e32 v248, v250
	v_permlane16_swap_b32_e32 v249, v251
	global_store_dwordx4 v[252:253], v[248:251], off
	s_nop 1
	v_mul_f32_e32 v26, v23, v23
	global_store_dwordx4 v[72:73], v[22:25], off offset:512
	v_fmac_f32_e32 v26, v22, v22
	v_mul_f32_e32 v27, v25, v25
	v_pk_mul_f32 v[22:23], v[188:189], v[22:23]
	v_fmac_f32_e32 v27, v24, v24
	v_pk_mul_f32 v[24:25], v[186:187], v[24:25]
	v_cvt_pk_bf16_f32 v248, v22, v23
	s_waitcnt vmcnt(8)
	v_pk_fma_f32 v[20:21], v[20:21], v[52:53], v[68:69]
	v_cvt_pk_bf16_f32 v249, v24, v25
	v_pk_fma_f32 v[18:19], v[18:19], v[50:51], v[66:67]
	v_add_f32_e32 v32, v32, v33
	v_mul_f32_e32 v22, v19, v19
	v_mul_f32_e32 v23, v21, v21
	v_add_f32_e32 v32, v86, v32
	v_add_f32_e32 v26, v26, v27
	v_fmac_f32_e32 v22, v18, v18
	v_fmac_f32_e32 v23, v20, v20
	v_add_f32_e32 v26, v32, v26
	global_store_dwordx4 v[72:73], v[18:21], off offset:576
	v_add_f32_e32 v22, v22, v23
	v_add_f32_e32 v22, v26, v22
	v_pk_mul_f32 v[18:19], v[182:183], v[18:19]
	v_pk_mul_f32 v[20:21], v[184:185], v[20:21]
	v_cvt_pk_bf16_f32 v250, v18, v19
	s_nop 0
	v_cvt_pk_bf16_f32 v251, v20, v21
	v_lshl_add_u64 v[252:253], v[236:237], 0, v[30:31]
	s_nop 0
	v_permlane16_swap_b32_e32 v248, v250
	v_permlane16_swap_b32_e32 v249, v251
	global_store_dwordx4 v[252:253], v[248:251], off offset:256
	s_nop 1
	ds_swizzle_b32 v18, v22 offset:swizzle(SWAP,16)
	s_waitcnt lgkmcnt(0)
	v_add_f32_e32 v18, v22, v18
	v_mov_b32_e32 v19, v18
	s_nop 1
	v_permlane32_swap_b32_e32 v18, v19
	s_and_saveexec_b64 s[4:5], s[36:37]
	s_cbranch_execz .LBB0_1216
	v_add_f32_e32 v18, v18, v19
	global_atomic_add_f32 v[134:135], v18, off offset:640
.LBB0_1216:
	s_or_b64 exec, exec, s[4:5]
	v_lshlrev_b64 v[18:19], 11, v[70:71]
	v_lshl_add_u64 v[18:19], v[18:19], 0, v[180:181]
	s_waitcnt vmcnt(9)
	v_pk_fma_f32 v[16:17], v[16:17], v[64:65], v[48:49]
	v_pk_fma_f32 v[14:15], v[14:15], v[62:63], v[46:47]
	v_lshl_add_u64 v[20:21], v[18:19], 2, s[40:41]
	v_mul_f32_e32 v22, v15, v15
	v_mul_f32_e32 v23, v17, v17
	global_store_dwordx4 v[20:21], v[14:17], off
	v_fmac_f32_e32 v22, v14, v14
	v_fmac_f32_e32 v23, v16, v16
	v_pk_mul_f32 v[16:17], v[194:195], v[16:17]
	v_pk_mul_f32 v[14:15], v[196:197], v[14:15]
	s_waitcnt vmcnt(9)
	v_pk_fma_f32 v[10:11], v[10:11], v[58:59], v[42:43]
	v_cvt_pk_bf16_f32 v248, v14, v15
	v_cvt_pk_bf16_f32 v249, v16, v17
	v_lshl_add_u64 v[16:17], v[18:19], 1, s[42:43]
	v_pk_fma_f32 v[12:13], v[12:13], v[60:61], v[44:45]
	v_mul_f32_e32 v14, v11, v11
	global_store_dwordx4 v[20:21], v[10:13], off offset:64
	v_fmac_f32_e32 v14, v10, v10
	v_mul_f32_e32 v15, v13, v13
	v_pk_mul_f32 v[10:11], v[192:193], v[10:11]
	s_waitcnt vmcnt(9)
	v_pk_fma_f32 v[6:7], v[6:7], v[54:55], v[38:39]
	v_cvt_pk_bf16_f32 v250, v10, v11
	v_fmac_f32_e32 v15, v12, v12
	v_pk_mul_f32 v[12:13], v[190:191], v[12:13]
	v_pk_fma_f32 v[8:9], v[8:9], v[56:57], v[40:41]
	v_cvt_pk_bf16_f32 v251, v12, v13
	v_lshl_add_u64 v[252:253], v[236:237], 0, v[16:17]
	s_nop 0
	v_permlane16_swap_b32_e32 v248, v250
	v_permlane16_swap_b32_e32 v249, v251
	global_store_dwordx4 v[252:253], v[248:251], off
	s_nop 1
	v_mul_f32_e32 v10, v7, v7
	global_store_dwordx4 v[20:21], v[6:9], off offset:512
	v_fmac_f32_e32 v10, v6, v6
	v_mul_f32_e32 v11, v9, v9
	v_pk_mul_f32 v[6:7], v[188:189], v[6:7]
	v_fmac_f32_e32 v11, v8, v8
	v_pk_mul_f32 v[8:9], v[186:187], v[8:9]
	v_cvt_pk_bf16_f32 v248, v6, v7
	s_waitcnt vmcnt(10)
	v_pk_fma_f32 v[4:5], v[4:5], v[52:53], v[36:37]
	v_cvt_pk_bf16_f32 v249, v8, v9
	v_pk_fma_f32 v[2:3], v[2:3], v[50:51], v[34:35]
	v_add_f32_e32 v22, v22, v23
	v_add_f32_e32 v14, v14, v15
	v_mul_f32_e32 v6, v3, v3
	v_mul_f32_e32 v7, v5, v5
	v_add_f32_e32 v14, v22, v14
	v_add_f32_e32 v10, v10, v11
	v_fmac_f32_e32 v6, v2, v2
	v_fmac_f32_e32 v7, v4, v4
	v_add_f32_e32 v10, v14, v10
	v_add_f32_e32 v6, v6, v7
	v_add_f32_e32 v6, v10, v6
	ds_swizzle_b32 v7, v6 offset:swizzle(SWAP,16)
	global_store_dwordx4 v[20:21], v[2:5], off offset:576
	s_nop 1
	v_pk_mul_f32 v[2:3], v[182:183], v[2:3]
	v_pk_mul_f32 v[4:5], v[184:185], v[4:5]
	v_cvt_pk_bf16_f32 v250, v2, v3
	s_nop 0
	v_cvt_pk_bf16_f32 v251, v4, v5
	v_lshl_add_u64 v[252:253], v[236:237], 0, v[16:17]
	s_nop 0
	v_permlane16_swap_b32_e32 v248, v250
	v_permlane16_swap_b32_e32 v249, v251
	global_store_dwordx4 v[252:253], v[248:251], off offset:256
	s_nop 1
	s_waitcnt lgkmcnt(0)
	v_add_f32_e32 v2, v6, v7
	v_mov_b32_e32 v3, v2
	s_nop 1
	v_permlane32_swap_b32_e32 v2, v3
	s_and_saveexec_b64 s[4:5], s[36:37]
	s_cbranch_execz .LBB0_1218
	v_add_f32_e32 v2, v2, v3
	global_atomic_add_f32 v[134:135], v2, off offset:704

; #define PG8_STAGE(bufoff, gbase, voff) do { _Pragma("unroll") for (int _i = 0; _i < 2; ++_i) \
;         __builtin_amdgcn_global_load_lds((const unsigned*)((const char*)(gbase) + (voff)[_i]), (LAS unsigned*)(lds + (bufoff) + ldsw + _i * 8192), 16, 0, 0); } while (0)
; #define PG8_WAIT_V(n) asm volatile("s_waitcnt vmcnt(" #n ")" ::: "memory")
; #define PG8_BAR __builtin_amdgcn_s_barrier()
; template <class Epi, int AMODE>
; __device__ __forceinline__ void gemm_phase(LAS unsigned char* lds, const Gemm g, const StaticOrder& S, const Epi& E, int stagger_us, int tid_in) {
;     ...
;     const char* cA = Abase + (size_t)cur.pm * tstepA; const char* cB = (const char*)g.Bt + (size_t)cur.pn * tstepB;
;     PG8_STAGE(PG8_SB(0, 0), cB, voffB); PG8_STAGE(PG8_SB(0, 1), cB + hstepB, voffB); PG8_STAGE(PG8_SA(0, 0), cA, voffA); PG8_STAGE(PG8_SA(0, 1), cA + hstepA, voffA);
;     if (wr == 1) PG8_BAR;
;     PG8_WAIT_V(2); PG8_BAR;
;     PG8_STAGE(PG8_SB(1, 0), cB + kstep, voffB); PG8_STAGE(PG8_SA(1, 0), cA + kstep, voffA); PG8_STAGE(PG8_SB(1, 1), cB + hstepB + kstep, voffB);
;     PG8_WAIT_V(6); PG8_BAR;
.LBB0_1488:
	s_lshl_b32 s30, s26, 11
	s_addk_i32 s30, 0x800
	s_ashr_i32 s31, s30, 31
	s_lshl_b64 s[30:31], s[30:31], 2
	s_waitcnt lgkmcnt(0)
	s_add_u32 s44, s6, s30
	s_addc_u32 s45, s7, s31
	s_add_u32 s67, s58, 0x92000
	s_addc_u32 s69, s59, 0
	s_lshl_b32 s6, s26, 1
	s_add_i32 s6, s6, 2
	s_mul_hi_i32 s7, s6, 0x28400
	s_mul_i32 s6, s6, 0x28400
	s_add_u32 s6, s50, s6
	v_bfe_u32 v18, v160, 4, 2
	s_addc_u32 s7, s51, s7
	v_and_b32_e32 v19, 15, v160
	v_lshlrev_b32_e32 v20, 4, v18
	s_add_u32 s52, s6, 0x100000
	v_lshl_or_b32 v208, s29, 6, v19
	v_lshl_or_b32 v19, v19, 6, v20
	v_lshlrev_b32_e32 v20, 2, v160
	s_addc_u32 s53, s7, 0
	s_lshl_b32 s6, s29, 13
	v_and_b32_e32 v20, 32, v20
	v_bitop3_b32 v21, v19, s6, v20 bitop3:0xde
	s_lshl_b32 s6, s28, 5
	s_and_b32 s26, s6, 0x60
	s_lshl_b32 s6, s26, 7
	s_add_u32 s50, s50, 0x17100000
	s_addc_u32 s51, s51, 0
	s_add_i32 m0, s13, 0x18000
	v_lshl_add_u64 v[8:9], v[8:9], 0, s[74:75]
	s_waitcnt vmcnt(2)
	s_barrier
	global_load_lds_dwordx4 v[8:9], off
	v_lshl_add_u64 v[6:7], v[6:7], 0, s[74:75]
	s_add_i32 m0, s13, 0x1a000
	s_add_i32 s79, s13, 0x8000
	s_add_i32 s83, s13, 0xa000
	v_bitop3_b32 v209, v19, s6, v20 bitop3:0xde
	global_load_lds_dwordx4 v[6:7], off
	v_lshl_add_u64 v[2:3], v[2:3], 0, s[74:75]
	s_mov_b32 m0, s79
	s_add_u32 s6, s4, 0x158080
	global_load_lds_dwordx4 v[2:3], off
	v_lshl_add_u64 v[2:3], v[4:5], 0, s[74:75]
	s_mov_b32 m0, s83
	s_addc_u32 s7, s5, 0
	global_load_lds_dwordx4 v[2:3], off
	s_add_i32 m0, s13, 0x1c000
	v_lshl_add_u64 v[2:3], s[6:7], 0, v[0:1]
	global_load_lds_dwordx4 v[2:3], off
	v_lshl_add_u64 v[2:3], s[6:7], 0, v[174:175]
	s_add_i32 m0, s13, 0x1e000
	v_lshl_or_b32 v214, v18, 2, s26
	v_and_b32_e32 v236, 1, v18
	v_mul_u32_u24_e32 v236, 24, v236
	v_mov_b32_e32 v237, 0
	global_load_lds_dwordx4 v[2:3], off
	s_movk_i32 s26, 0x1580
	s_cmpk_lt_u32 s27, 0x100
	v_lshrrev_b32_e32 v3, 1, v15
	v_mul_lo_u32 v2, v14, s26
	s_mov_b32 s27, 0x15800
	v_mad_u64_u32 v[2:3], s[6:7], v3, s27, v[2:3]
	v_or_b32_e32 v2, v2, v16
	v_add_lshl_u32 v2, v2, v17, 1
	v_mov_b32_e32 v3, v1
	s_mov_b64 s[28:29], 0x158080
	v_lshl_add_u64 v[176:177], v[2:3], 0, s[28:29]
	v_lshrrev_b32_e32 v3, 1, v10
	v_mul_lo_u32 v2, v11, s26
	v_mad_u64_u32 v[2:3], s[6:7], v3, s27, v[2:3]
	s_waitcnt vmcnt(6)
	v_or_b32_e32 v2, v2, v12
	v_add_lshl_u32 v2, v2, v13, 1
	v_mov_b32_e32 v3, v1
	s_cselect_b64 s[54:55], -1, 0
	s_mov_b32 s85, 0
	v_cmp_eq_u32_e64 s[36:37], 0, v18
	s_ashr_i32 s87, s8, 31
	v_lshl_add_u64 v[178:179], v[2:3], 0, s[28:29]
	v_add_u32_e32 v215, 0, v21
	v_readlane_b32 s93, v255, 50
	v_readlane_b32 s92, v255, 47
	s_barrier
	s_branch .LBB0_1491

;     __device__ __forceinline__ void operator()(const f32x4 (&acc)[2][2][4][2], const Unit& u, int wr, int wc, int fr, int fq) const {
;         const int row0 = u.pm * BM + wr * 64 + fr, col0 = u.pn * BM + wc * 32 + 4 * fq;
;         const float* base = (u.pm * BM < TOKP) ? base_p : base_s;
;         const int b = batch_of(u.pm * BM);
;         const float* gp = gate + (size_t)b * (6 * DM) + col0;
;         f32x4 gv[2][2], gg[2][2], gs[2][2];
; #pragma unroll
;         for (int bj = 0; bj < 2; ++bj)
; #pragma unroll
;             for (int n = 0; n < 2; ++n) { gv[bj][n] = LDG(f32x4, gp + bj * HALF + n * 16);
;                 if (NEXT) { gg[bj][n] = LDG(f32x4, gain + col0 + bj * HALF + n * 16); gs[bj][n] = LDG(f32x4, scale + (size_t)b * (6 * DM) + col0 + bj * HALF + n * 16); } }
;         f32x4 bs0[2][2][2];
; #pragma unroll
;         for (int mm = 0; mm < 2; ++mm)
; #pragma unroll
;             for (int bj = 0; bj < 2; ++bj)
; #pragma unroll
;                 for (int n = 0; n < 2; ++n) { const size_t o_ = (size_t)(row0 + mm * 16) * DM + col0 + bj * HALF + n * 16;
;                     if (RES_BF16) { const u32x2 r = LDG(u32x2, xres + o_); bs0[mm][bj][n] = (f32x4){bf_lo(r.x), bf_hi(r.x), bf_lo(r.y), bf_hi(r.y)}; }
;                     else bs0[mm][bj][n] = LDG(f32x4, base + o_); }
;         asm volatile("" ::: "memory");
;         if (NEXT) {
; #pragma unroll
;             for (int bj = 0; bj < 2; ++bj)
; #pragma unroll
;                 for (int n = 0; n < 2; ++n) gg[bj][n] = gg[bj][n] * (gs[bj][n] + 1.0f); }
; #pragma unroll
;         for (int ai = 0; ai < 2; ++ai)
; #pragma unroll
;         for (int mp = 0; mp < 2; ++mp) {
;             f32x4 bs[2][2][2];
; #pragma unroll
;             for (int mm = 0; mm < 2; ++mm)
; #pragma unroll
;                 for (int bj = 0; bj < 2; ++bj)
; #pragma unroll
;                     for (int n = 0; n < 2; ++n) { const size_t o_ = (size_t)(row0 + ai * HALF + (2 * mp + mm) * 16) * DM + col0 + bj * HALF + n * 16;
;                         if (ai == 0 && mp == 0) bs[mm][bj][n] = bs0[mm][bj][n];
;                         else if (RES_BF16) { const u32x2 r = LDG(u32x2, xres + o_); bs[mm][bj][n] = (f32x4){bf_lo(r.x), bf_hi(r.x), bf_lo(r.y), bf_hi(r.y)}; }
;                         else bs[mm][bj][n] = LDG(f32x4, base + o_); }
;             asm volatile("" ::: "memory");
; #pragma unroll
.LBB0_1501:
	s_lshl_b32 s6, s92, 8
	s_add_i32 s5, s6, 0xffffe000
	s_lshr_b32 s5, s5, 12
	s_ashr_i32 s4, s92, 3
	s_add_i32 s5, s5, 4
	s_cmp_lt_i32 s92, 32
	s_cselect_b32 s4, s4, s5
	v_lshl_or_b32 v182, s93, 8, v214
	s_mul_i32 s27, s4, 0xc000
	s_mul_hi_i32 s7, s4, 0xc000
	s_add_u32 s4, s63, s27
	v_ashrrev_i32_e32 v183, 31, v182
	s_addc_u32 s5, s72, s7
	v_lshlrev_b64 v[146:147], 2, v[182:183]
	v_lshl_add_u64 v[50:51], s[4:5], 0, v[146:147]
	s_add_u32 s4, s67, s27
	s_addc_u32 s5, s69, s7
	v_add_u32_e32 v180, s6, v208
	v_lshl_add_u64 v[148:149], s[44:45], 0, v[146:147]
	v_lshl_add_u64 v[150:151], s[4:5], 0, v[146:147]
	global_load_dwordx4 v[62:65], v[50:51], off
	global_load_dwordx4 v[184:187], v[148:149], off
	global_load_dwordx4 v[188:191], v[150:151], off
	global_load_dwordx4 v[58:61], v[50:51], off offset:64
	global_load_dwordx4 v[210:213], v[148:149], off offset:64
	global_load_dwordx4 v[192:195], v[150:151], off offset:64
	global_load_dwordx4 v[54:57], v[50:51], off offset:512
	global_load_dwordx4 v[216:219], v[148:149], off offset:512
	global_load_dwordx4 v[220:223], v[150:151], off offset:512
	s_nop 0
	global_load_dwordx4 v[50:53], v[50:51], off offset:576
	s_nop 0
	global_load_dwordx4 v[240:243], v[148:149], off offset:576
	global_load_dwordx4 v[244:247], v[150:151], off offset:576
	v_ashrrev_i32_e32 v181, 31, v180
	v_lshl_add_u64 v[200:201], s[48:49], 0, v[146:147]
	v_lshlrev_b64 v[146:147], 13, v[180:181]
	v_lshl_add_u64 v[206:207], v[200:201], 0, v[146:147]
	global_load_dwordx4 v[248:251], v[206:207], off
	global_load_dwordx4 v[170:173], v[206:207], off offset:64
	global_load_dwordx4 v[166:169], v[206:207], off offset:512
	global_load_dwordx4 v[162:165], v[206:207], off offset:576
	v_or_b32_e32 v204, 16, v180
	v_ashrrev_i32_e32 v205, 31, v204
	v_lshlrev_b64 v[146:147], 13, v[204:205]
	v_lshl_add_u64 v[202:203], v[200:201], 0, v[146:147]
	global_load_dwordx4 v[158:161], v[202:203], off
	global_load_dwordx4 v[154:157], v[202:203], off offset:64
	global_load_dwordx4 v[150:153], v[202:203], off offset:512
	global_load_dwordx4 v[146:149], v[202:203], off offset:576
	s_waitcnt vmcnt(0)
	v_pk_add_f32 v[188:189], v[188:189], 1.0 op_sel_hi:[1,0]
	v_pk_add_f32 v[190:191], v[190:191], 1.0 op_sel_hi:[1,0]
	v_pk_mul_f32 v[198:199], v[184:185], v[188:189]
	v_pk_add_f32 v[184:185], v[194:195], 1.0 op_sel_hi:[1,0]
	v_pk_mul_f32 v[196:197], v[186:187], v[190:191]
	v_pk_add_f32 v[186:187], v[192:193], 1.0 op_sel_hi:[1,0]
	v_pk_mul_f32 v[192:193], v[212:213], v[184:185]
	v_pk_add_f32 v[184:185], v[222:223], 1.0 op_sel_hi:[1,0]
	v_pk_mul_f32 v[194:195], v[210:211], v[186:187]
	v_pk_add_f32 v[186:187], v[220:221], 1.0 op_sel_hi:[1,0]
	v_pk_mul_f32 v[188:189], v[218:219], v[184:185]
	v_pk_add_f32 v[184:185], v[246:247], 1.0 op_sel_hi:[1,0]
	v_pk_add_f32 v[210:211], v[244:245], 1.0 op_sel_hi:[1,0]
	v_pk_fma_f32 v[144:145], v[144:145], v[64:65], v[250:251]
	v_pk_fma_f32 v[142:143], v[142:143], v[62:63], v[248:249]
	v_pk_mul_f32 v[190:191], v[216:217], v[186:187]
	v_pk_mul_f32 v[186:187], v[242:243], v[184:185]
	v_pk_mul_f32 v[184:185], v[240:241], v[210:211]
	v_lshlrev_b64 v[210:211], 11, v[180:181]
	v_mul_f32_e32 v212, v143, v143
	v_mul_f32_e32 v213, v145, v145
	v_lshl_add_u64 v[210:211], v[210:211], 0, v[182:183]
	global_store_dwordx4 v[206:207], v[142:145], off
	v_fmac_f32_e32 v212, v142, v142
	v_fmac_f32_e32 v213, v144, v144
	v_pk_mul_f32 v[144:145], v[196:197], v[144:145]
	v_pk_mul_f32 v[142:143], v[198:199], v[142:143]
	v_pk_fma_f32 v[138:139], v[138:139], v[58:59], v[170:171]
	v_add_f32_e32 v216, v212, v213
	v_cvt_pk_bf16_f32 v240, v142, v143
	v_cvt_pk_bf16_f32 v241, v144, v145
	v_lshl_add_u64 v[142:143], v[210:211], 1, s[50:51]
	v_pk_fma_f32 v[140:141], v[140:141], v[60:61], v[172:173]
	v_mul_f32_e32 v144, v139, v139
	global_store_dwordx4 v[206:207], v[138:141], off offset:64
	v_fmac_f32_e32 v144, v138, v138
	v_mul_f32_e32 v145, v141, v141
	v_pk_mul_f32 v[138:139], v[194:195], v[138:139]
	v_pk_fma_f32 v[134:135], v[134:135], v[54:55], v[166:167]
	v_cvt_pk_bf16_f32 v242, v138, v139
	v_fmac_f32_e32 v145, v140, v140
	v_pk_mul_f32 v[140:141], v[192:193], v[140:141]
	v_pk_fma_f32 v[136:137], v[136:137], v[56:57], v[168:169]
	v_cvt_pk_bf16_f32 v243, v140, v141
	v_lshl_add_u64 v[252:253], v[236:237], 0, v[142:143]
	s_nop 0
	v_permlane16_swap_b32_e32 v240, v242
	v_permlane16_swap_b32_e32 v241, v243
	global_store_dwordx4 v[252:253], v[240:243], off
	s_nop 1
	v_mul_f32_e32 v138, v135, v135
	global_store_dwordx4 v[206:207], v[134:137], off offset:512
	v_fmac_f32_e32 v138, v134, v134
	v_mul_f32_e32 v139, v137, v137
	v_pk_mul_f32 v[134:135], v[190:191], v[134:135]
	v_fmac_f32_e32 v139, v136, v136
	v_pk_mul_f32 v[136:137], v[188:189], v[136:137]
	v_cvt_pk_bf16_f32 v240, v134, v135
	v_pk_fma_f32 v[132:133], v[132:133], v[52:53], v[164:165]
	v_cvt_pk_bf16_f32 v241, v136, v137
	v_pk_fma_f32 v[130:131], v[130:131], v[50:51], v[162:163]
	v_add_f32_e32 v144, v144, v145
	v_mul_f32_e32 v134, v131, v131
	v_mul_f32_e32 v135, v133, v133
	v_add_f32_e32 v144, v216, v144
	v_add_f32_e32 v138, v138, v139
	v_fmac_f32_e32 v134, v130, v130
	v_fmac_f32_e32 v135, v132, v132
	v_add_f32_e32 v138, v144, v138
	global_store_dwordx4 v[206:207], v[130:133], off offset:576
	v_add_f32_e32 v134, v134, v135
	v_add_f32_e32 v134, v138, v134
	v_pk_mul_f32 v[130:131], v[184:185], v[130:131]
	v_pk_mul_f32 v[132:133], v[186:187], v[132:133]
	v_cvt_pk_bf16_f32 v242, v130, v131
	s_nop 0
	v_cvt_pk_bf16_f32 v243, v132, v133
	v_lshl_add_u64 v[252:253], v[236:237], 0, v[142:143]
	s_nop 0
	v_permlane16_swap_b32_e32 v240, v242
	v_permlane16_swap_b32_e32 v241, v243
	global_store_dwordx4 v[252:253], v[240:243], off offset:256
	s_nop 1
	ds_swizzle_b32 v130, v134 offset:swizzle(SWAP,16)
	s_waitcnt lgkmcnt(0)
	v_add_f32_e32 v130, v134, v130
	v_mov_b32_e32 v131, v130
	s_nop 1
	v_permlane32_swap_b32_e32 v130, v131
	s_and_saveexec_b64 s[4:5], s[36:37]
	s_cbranch_execz .LBB0_1503
	v_lshl_add_u64 v[132:133], v[180:181], 2, s[52:53]
	v_add_f32_e32 v130, v130, v131
	global_atomic_add_f32 v[132:133], v130, off
; __device__ __forceinline__ unsigned cvt_pk_bf16(float lo, float hi) { unsigned r; asm volatile("v_cvt_pk_bf16_f32 %0, %1, %2" : "=v"(r) : "v"(lo), "v"(hi)); return r; }
; __device__ __forceinline__ float bf_lo(unsigned w) { return __uint_as_float(w << 16); }
; __device__ __forceinline__ float bf_hi(unsigned w) { return __uint_as_float(w & 0xffff0000u); }
; template <int O> __device__ __forceinline__ float swz_xor(float v) { return __int_as_float(__builtin_amdgcn_ds_swizzle(__float_as_int(v), (O << 10) | 0x1F)); }
;     __device__ __forceinline__ void operator()(const f32x4 (&acc)[2][2][4][2], const Unit& u, int wr, int wc, int fr, int fq) const {
;     ...
;                     for (int n = 0; n < 2; ++n) { const size_t o_ = (size_t)(row0 + ai * HALF + (2 * mp + mm) * 16) * DM + col0 + bj * HALF + n * 16;
;                         if (ai == 0 && mp == 0) bs[mm][bj][n] = bs0[mm][bj][n];
;                         else if (RES_BF16) { const u32x2 r = LDG(u32x2, xres + o_); bs[mm][bj][n] = (f32x4){bf_lo(r.x), bf_hi(r.x), bf_lo(r.y), bf_hi(r.y)}; }
;                         else bs[mm][bj][n] = LDG(f32x4, base + o_); }
;             asm volatile("" ::: "memory");
; #pragma unroll
;             for (int mm = 0; mm < 2; ++mm) { const int m = 2 * mp + mm; const int row = row0 + ai * HALF + m * 16; const size_t off = (size_t)row * DM + col0; float ss = 0.f;
; #pragma unroll
;                 for (int bj = 0; bj < 2; ++bj)
; #pragma unroll
;                     for (int n = 0; n < 2; ++n) { const f32x4 xn = bs[mm][bj][n] + gv[bj][n] * acc[ai][bj][m][n];
;                         if (RES_BF16) { u32x2 w_; w_.x = cvt_pk_bf16(xn[0], xn[1]); w_.y = cvt_pk_bf16(xn[2], xn[3]); STG(u32x2, xres + off + bj * HALF + n * 16) = w_; }
;                         else STG(f32x4, out + off + bj * HALF + n * 16) = xn;
;                         if (NEXT) { ss += (xn[0] * xn[0] + xn[1] * xn[1]) + (xn[2] * xn[2] + xn[3] * xn[3]); const f32x4 y = xn * gg[bj][n];
;                             u32x2 w; w.x = cvt_pk_bf16(y[0], y[1]); w.y = cvt_pk_bf16(y[2], y[3]); STG(u32x2, xg + off + bj * HALF + n * 16) = w; } }
;                 if (NEXT) { ss += swz_xor<16>(ss); auto rr = __builtin_amdgcn_permlane32_swap(__float_as_uint(ss), __float_as_uint(ss), false, false); ss = __uint_as_float(rr[0]) + __uint_as_float(rr[1]);
;                     if (fq == 0) atomicAdd(ssq + row, ss); } }
.LBB0_1503:
	s_or_b64 exec, exec, s[4:5]
	v_pk_fma_f32 v[128:129], v[128:129], v[64:65], v[160:161]
	v_pk_fma_f32 v[126:127], v[126:127], v[62:63], v[158:159]
	v_lshlrev_b64 v[130:131], 11, v[204:205]
	v_mul_f32_e32 v132, v127, v127
	v_mul_f32_e32 v133, v129, v129
	v_lshl_add_u64 v[130:131], v[130:131], 0, v[182:183]
	global_store_dwordx4 v[202:203], v[126:129], off
	v_fmac_f32_e32 v132, v126, v126
	v_fmac_f32_e32 v133, v128, v128
	v_pk_mul_f32 v[128:129], v[196:197], v[128:129]
	v_pk_mul_f32 v[126:127], v[198:199], v[126:127]
	v_pk_fma_f32 v[122:123], v[122:123], v[58:59], v[154:155]
	v_cvt_pk_bf16_f32 v240, v126, v127
	v_cvt_pk_bf16_f32 v241, v128, v129
	v_lshl_add_u64 v[128:129], v[130:131], 1, s[50:51]
	v_pk_fma_f32 v[124:125], v[124:125], v[60:61], v[156:157]
	v_mul_f32_e32 v126, v123, v123
	global_store_dwordx4 v[202:203], v[122:125], off offset:64
	v_fmac_f32_e32 v126, v122, v122
	v_mul_f32_e32 v127, v125, v125
	v_pk_mul_f32 v[122:123], v[194:195], v[122:123]
	v_pk_fma_f32 v[118:119], v[118:119], v[54:55], v[150:151]
	v_cvt_pk_bf16_f32 v242, v122, v123
	v_fmac_f32_e32 v127, v124, v124
	v_pk_mul_f32 v[124:125], v[192:193], v[124:125]
	v_pk_fma_f32 v[120:121], v[120:121], v[56:57], v[152:153]
	v_cvt_pk_bf16_f32 v243, v124, v125
	v_lshl_add_u64 v[252:253], v[236:237], 0, v[128:129]
	s_nop 0
	v_permlane16_swap_b32_e32 v240, v242
	v_permlane16_swap_b32_e32 v241, v243
	global_store_dwordx4 v[252:253], v[240:243], off
	s_nop 1
	v_mul_f32_e32 v122, v119, v119
	global_store_dwordx4 v[202:203], v[118:121], off offset:512
	v_fmac_f32_e32 v122, v118, v118
	v_mul_f32_e32 v123, v121, v121
	v_pk_mul_f32 v[118:119], v[190:191], v[118:119]
	v_fmac_f32_e32 v123, v120, v120
	v_pk_mul_f32 v[120:121], v[188:189], v[120:121]
	v_cvt_pk_bf16_f32 v240, v118, v119
	v_pk_fma_f32 v[116:117], v[116:117], v[52:53], v[148:149]
	v_cvt_pk_bf16_f32 v241, v120, v121
	v_pk_fma_f32 v[114:115], v[114:115], v[50:51], v[146:147]
	v_add_f32_e32 v132, v132, v133
	v_add_f32_e32 v126, v126, v127
	v_mul_f32_e32 v118, v115, v115
	v_mul_f32_e32 v119, v117, v117
	v_add_f32_e32 v126, v132, v126
	v_add_f32_e32 v122, v122, v123
	v_fmac_f32_e32 v118, v114, v114
	v_fmac_f32_e32 v119, v116, v116
	v_add_f32_e32 v122, v126, v122
	v_add_f32_e32 v118, v118, v119
	v_add_f32_e32 v118, v122, v118
	ds_swizzle_b32 v119, v118 offset:swizzle(SWAP,16)
	global_store_dwordx4 v[202:203], v[114:117], off offset:576
	s_nop 1
	v_pk_mul_f32 v[114:115], v[184:185], v[114:115]
	v_pk_mul_f32 v[116:117], v[186:187], v[116:117]
	v_cvt_pk_bf16_f32 v242, v114, v115
	s_nop 0
	v_cvt_pk_bf16_f32 v243, v116, v117
	v_lshl_add_u64 v[252:253], v[236:237], 0, v[128:129]
	s_nop 0
	v_permlane16_swap_b32_e32 v240, v242
	v_permlane16_swap_b32_e32 v241, v243
	global_store_dwordx4 v[252:253], v[240:243], off offset:256
	s_nop 1
	s_waitcnt lgkmcnt(0)
	v_add_f32_e32 v114, v118, v119
	v_mov_b32_e32 v115, v114
	s_nop 1
	v_permlane32_swap_b32_e32 v114, v115
	s_and_saveexec_b64 s[4:5], s[36:37]
	s_cbranch_execz .LBB0_1505
	v_lshl_add_u64 v[116:117], v[180:181], 2, s[52:53]
	v_add_f32_e32 v114, v114, v115
	global_atomic_add_f32 v[116:117], v114, off offset:64
.LBB0_1505:
	s_or_b64 exec, exec, s[4:5]
	v_or_b32_e32 v152, 32, v180
	v_ashrrev_i32_e32 v153, 31, v152
	v_lshlrev_b64 v[114:115], 13, v[152:153]
	v_lshl_add_u64 v[138:139], v[200:201], 0, v[114:115]
	global_load_dwordx4 v[140:143], v[138:139], off
	global_load_dwordx4 v[144:147], v[138:139], off offset:64
	global_load_dwordx4 v[148:151], v[138:139], off offset:512
	global_load_dwordx4 v[130:133], v[138:139], off offset:576
	v_or_b32_e32 v136, 48, v180
	v_ashrrev_i32_e32 v137, 31, v136
	v_lshlrev_b64 v[114:115], 13, v[136:137]
	v_lshl_add_u64 v[134:135], v[200:201], 0, v[114:115]
	global_load_dwordx4 v[126:129], v[134:135], off
	global_load_dwordx4 v[122:125], v[134:135], off offset:64
	global_load_dwordx4 v[118:121], v[134:135], off offset:512
	global_load_dwordx4 v[114:117], v[134:135], off offset:576
	v_lshlrev_b64 v[152:153], 11, v[152:153]
	v_lshl_add_u64 v[152:153], v[152:153], 0, v[182:183]
	s_waitcnt vmcnt(7)
	v_pk_fma_f32 v[112:113], v[112:113], v[64:65], v[142:143]
	v_pk_fma_f32 v[110:111], v[110:111], v[62:63], v[140:141]
	v_mul_f32_e32 v141, v113, v113
	v_mul_f32_e32 v140, v111, v111
	global_store_dwordx4 v[138:139], v[110:113], off
	v_fmac_f32_e32 v140, v110, v110
	v_fmac_f32_e32 v141, v112, v112
	v_pk_mul_f32 v[112:113], v[196:197], v[112:113]
	v_pk_mul_f32 v[110:111], v[198:199], v[110:111]
	s_waitcnt vmcnt(7)
	v_pk_fma_f32 v[106:107], v[106:107], v[58:59], v[144:145]
	v_add_f32_e32 v142, v140, v141
	v_cvt_pk_bf16_f32 v240, v110, v111
	v_cvt_pk_bf16_f32 v241, v112, v113
	v_lshl_add_u64 v[110:111], v[152:153], 1, s[50:51]
	v_pk_fma_f32 v[108:109], v[108:109], v[60:61], v[146:147]
	v_mul_f32_e32 v112, v107, v107
	global_store_dwordx4 v[138:139], v[106:109], off offset:64
	v_fmac_f32_e32 v112, v106, v106
	v_mul_f32_e32 v113, v109, v109
	v_pk_mul_f32 v[106:107], v[194:195], v[106:107]
	s_waitcnt vmcnt(7)
	v_pk_fma_f32 v[102:103], v[102:103], v[54:55], v[148:149]
	v_cvt_pk_bf16_f32 v242, v106, v107
	v_fmac_f32_e32 v113, v108, v108
	v_pk_mul_f32 v[108:109], v[192:193], v[108:109]
	v_pk_fma_f32 v[104:105], v[104:105], v[56:57], v[150:151]
	v_cvt_pk_bf16_f32 v243, v108, v109
	v_lshl_add_u64 v[252:253], v[236:237], 0, v[110:111]
	s_nop 0
	v_permlane16_swap_b32_e32 v240, v242
	v_permlane16_swap_b32_e32 v241, v243
	global_store_dwordx4 v[252:253], v[240:243], off
	s_nop 1
	v_mul_f32_e32 v106, v103, v103
	global_store_dwordx4 v[138:139], v[102:105], off offset:512
	v_fmac_f32_e32 v106, v102, v102
	v_mul_f32_e32 v107, v105, v105
	v_pk_mul_f32 v[102:103], v[190:191], v[102:103]
	v_fmac_f32_e32 v107, v104, v104
	v_pk_mul_f32 v[104:105], v[188:189], v[104:105]
	v_cvt_pk_bf16_f32 v240, v102, v103
	s_waitcnt vmcnt(8)
	v_pk_fma_f32 v[100:101], v[100:101], v[52:53], v[132:133]
	v_cvt_pk_bf16_f32 v241, v104, v105
	v_pk_fma_f32 v[98:99], v[98:99], v[50:51], v[130:131]
	v_add_f32_e32 v112, v112, v113
	v_mul_f32_e32 v102, v99, v99
	v_mul_f32_e32 v103, v101, v101
	v_add_f32_e32 v112, v142, v112
	v_add_f32_e32 v106, v106, v107
	v_fmac_f32_e32 v102, v98, v98
	v_fmac_f32_e32 v103, v100, v100
	v_add_f32_e32 v106, v112, v106
	global_store_dwordx4 v[138:139], v[98:101], off offset:576
	v_add_f32_e32 v102, v102, v103
	v_add_f32_e32 v102, v106, v102
	v_pk_mul_f32 v[98:99], v[184:185], v[98:99]
	v_pk_mul_f32 v[100:101], v[186:187], v[100:101]
	v_cvt_pk_bf16_f32 v242, v98, v99
	s_nop 0
	v_cvt_pk_bf16_f32 v243, v100, v101
	v_lshl_add_u64 v[252:253], v[236:237], 0, v[110:111]
	s_nop 0
	v_permlane16_swap_b32_e32 v240, v242
	v_permlane16_swap_b32_e32 v241, v243
	global_store_dwordx4 v[252:253], v[240:243], off offset:256
	s_nop 1
	ds_swizzle_b32 v98, v102 offset:swizzle(SWAP,16)
	s_waitcnt lgkmcnt(0)
	v_add_f32_e32 v98, v102, v98
	v_mov_b32_e32 v99, v98
	s_nop 1
	v_permlane32_swap_b32_e32 v98, v99
	s_and_saveexec_b64 s[4:5], s[36:37]
	s_cbranch_execz .LBB0_1507
; __device__ __forceinline__ unsigned cvt_pk_bf16(float lo, float hi) { unsigned r; asm volatile("v_cvt_pk_bf16_f32 %0, %1, %2" : "=v"(r) : "v"(lo), "v"(hi)); return r; }
; __device__ __forceinline__ float bf_lo(unsigned w) { return __uint_as_float(w << 16); }
; __device__ __forceinline__ float bf_hi(unsigned w) { return __uint_as_float(w & 0xffff0000u); }
; template <int O> __device__ __forceinline__ float swz_xor(float v) { return __int_as_float(__builtin_amdgcn_ds_swizzle(__float_as_int(v), (O << 10) | 0x1F)); }
;     __device__ __forceinline__ void operator()(const f32x4 (&acc)[2][2][4][2], const Unit& u, int wr, int wc, int fr, int fq) const {
;     ...
;                     for (int n = 0; n < 2; ++n) { const size_t o_ = (size_t)(row0 + ai * HALF + (2 * mp + mm) * 16) * DM + col0 + bj * HALF + n * 16;
;                         if (ai == 0 && mp == 0) bs[mm][bj][n] = bs0[mm][bj][n];
;                         else if (RES_BF16) { const u32x2 r = LDG(u32x2, xres + o_); bs[mm][bj][n] = (f32x4){bf_lo(r.x), bf_hi(r.x), bf_lo(r.y), bf_hi(r.y)}; }
;                         else bs[mm][bj][n] = LDG(f32x4, base + o_); }
;             asm volatile("" ::: "memory");
; #pragma unroll
;             for (int mm = 0; mm < 2; ++mm) { const int m = 2 * mp + mm; const int row = row0 + ai * HALF + m * 16; const size_t off = (size_t)row * DM + col0; float ss = 0.f;
; #pragma unroll
;                 for (int bj = 0; bj < 2; ++bj)
; #pragma unroll
;                     for (int n = 0; n < 2; ++n) { const f32x4 xn = bs[mm][bj][n] + gv[bj][n] * acc[ai][bj][m][n];
;                         if (RES_BF16) { u32x2 w_; w_.x = cvt_pk_bf16(xn[0], xn[1]); w_.y = cvt_pk_bf16(xn[2], xn[3]); STG(u32x2, xres + off + bj * HALF + n * 16) = w_; }
;                         else STG(f32x4, out + off + bj * HALF + n * 16) = xn;
;                         if (NEXT) { ss += (xn[0] * xn[0] + xn[1] * xn[1]) + (xn[2] * xn[2] + xn[3] * xn[3]); const f32x4 y = xn * gg[bj][n];
;                             u32x2 w; w.x = cvt_pk_bf16(y[0], y[1]); w.y = cvt_pk_bf16(y[2], y[3]); STG(u32x2, xg + off + bj * HALF + n * 16) = w; } }
;                 if (NEXT) { ss += swz_xor<16>(ss); auto rr = __builtin_amdgcn_permlane32_swap(__float_as_uint(ss), __float_as_uint(ss), false, false); ss = __uint_as_float(rr[0]) + __uint_as_float(rr[1]);
;                     if (fq == 0) atomicAdd(ssq + row, ss); } }
	v_lshl_add_u64 v[100:101], v[180:181], 2, s[52:53]
	v_add_f32_e32 v98, v98, v99
	global_atomic_add_f32 v[100:101], v98, off offset:128
.LBB0_1507:
	s_or_b64 exec, exec, s[4:5]
	s_waitcnt vmcnt(9)
	v_pk_fma_f32 v[96:97], v[96:97], v[64:65], v[128:129]
	v_pk_fma_f32 v[94:95], v[94:95], v[62:63], v[126:127]
	v_lshlrev_b64 v[98:99], 11, v[136:137]
	v_mul_f32_e32 v100, v95, v95
	v_mul_f32_e32 v101, v97, v97
	v_lshl_add_u64 v[98:99], v[98:99], 0, v[182:183]
	global_store_dwordx4 v[134:135], v[94:97], off
	v_fmac_f32_e32 v100, v94, v94
	v_fmac_f32_e32 v101, v96, v96
	v_pk_mul_f32 v[96:97], v[196:197], v[96:97]
	v_pk_mul_f32 v[94:95], v[198:199], v[94:95]
	s_waitcnt vmcnt(9)
	v_pk_fma_f32 v[90:91], v[90:91], v[58:59], v[122:123]
	v_cvt_pk_bf16_f32 v240, v94, v95
	v_cvt_pk_bf16_f32 v241, v96, v97
	v_lshl_add_u64 v[96:97], v[98:99], 1, s[50:51]
	v_pk_fma_f32 v[92:93], v[92:93], v[60:61], v[124:125]
	v_mul_f32_e32 v94, v91, v91
	global_store_dwordx4 v[134:135], v[90:93], off offset:64
	v_fmac_f32_e32 v94, v90, v90
	v_mul_f32_e32 v95, v93, v93
	v_pk_mul_f32 v[90:91], v[194:195], v[90:91]
	s_waitcnt vmcnt(9)
	v_pk_fma_f32 v[86:87], v[86:87], v[54:55], v[118:119]
	v_cvt_pk_bf16_f32 v242, v90, v91
	v_fmac_f32_e32 v95, v92, v92
	v_pk_mul_f32 v[92:93], v[192:193], v[92:93]
	v_pk_fma_f32 v[88:89], v[88:89], v[56:57], v[120:121]
	v_cvt_pk_bf16_f32 v243, v92, v93
	v_lshl_add_u64 v[252:253], v[236:237], 0, v[96:97]
	s_nop 0
	v_permlane16_swap_b32_e32 v240, v242
	v_permlane16_swap_b32_e32 v241, v243
	global_store_dwordx4 v[252:253], v[240:243], off
	s_nop 1
	v_mul_f32_e32 v90, v87, v87
	global_store_dwordx4 v[134:135], v[86:89], off offset:512
	v_fmac_f32_e32 v90, v86, v86
	v_mul_f32_e32 v91, v89, v89
	v_pk_mul_f32 v[86:87], v[190:191], v[86:87]
	v_fmac_f32_e32 v91, v88, v88
	v_pk_mul_f32 v[88:89], v[188:189], v[88:89]
	v_cvt_pk_bf16_f32 v240, v86, v87
	s_waitcnt vmcnt(10)
	v_pk_fma_f32 v[84:85], v[84:85], v[52:53], v[116:117]
	v_cvt_pk_bf16_f32 v241, v88, v89
	v_pk_fma_f32 v[82:83], v[82:83], v[50:51], v[114:115]
	v_add_f32_e32 v100, v100, v101
	v_add_f32_e32 v94, v94, v95
	v_mul_f32_e32 v86, v83, v83
	v_mul_f32_e32 v87, v85, v85
	v_add_f32_e32 v94, v100, v94
	v_add_f32_e32 v90, v90, v91
	v_fmac_f32_e32 v86, v82, v82
	v_fmac_f32_e32 v87, v84, v84
	v_add_f32_e32 v90, v94, v90
	v_add_f32_e32 v86, v86, v87
	v_add_f32_e32 v86, v90, v86
	ds_swizzle_b32 v87, v86 offset:swizzle(SWAP,16)
	global_store_dwordx4 v[134:135], v[82:85], off offset:576
	s_nop 1
	v_pk_mul_f32 v[82:83], v[184:185], v[82:83]
	v_pk_mul_f32 v[84:85], v[186:187], v[84:85]
	v_cvt_pk_bf16_f32 v242, v82, v83
	s_nop 0
	v_cvt_pk_bf16_f32 v243, v84, v85
	v_lshl_add_u64 v[252:253], v[236:237], 0, v[96:97]
	s_nop 0
	v_permlane16_swap_b32_e32 v240, v242
	v_permlane16_swap_b32_e32 v241, v243
	global_store_dwordx4 v[252:253], v[240:243], off offset:256
	s_nop 1
	s_waitcnt lgkmcnt(0)
	v_add_f32_e32 v82, v86, v87
	v_mov_b32_e32 v83, v82
	s_nop 1
	v_permlane32_swap_b32_e32 v82, v83
	s_and_saveexec_b64 s[4:5], s[36:37]
	s_cbranch_execz .LBB0_1509
	v_lshl_add_u64 v[84:85], v[180:181], 2, s[52:53]
	v_add_f32_e32 v82, v82, v83
	global_atomic_add_f32 v[84:85], v82, off offset:192
.LBB0_1509:
	s_or_b64 exec, exec, s[4:5]
	v_add_u32_e32 v120, 0x80, v180
	v_ashrrev_i32_e32 v121, 31, v120
	v_lshlrev_b64 v[82:83], 13, v[120:121]
	v_lshl_add_u64 v[106:107], v[200:201], 0, v[82:83]
	global_load_dwordx4 v[108:111], v[106:107], off
	global_load_dwordx4 v[112:115], v[106:107], off offset:64
	global_load_dwordx4 v[116:119], v[106:107], off offset:512
	global_load_dwordx4 v[98:101], v[106:107], off offset:576
	v_add_u32_e32 v104, 0x90, v180
	v_ashrrev_i32_e32 v105, 31, v104
	v_lshlrev_b64 v[82:83], 13, v[104:105]
	v_lshl_add_u64 v[102:103], v[200:201], 0, v[82:83]
	global_load_dwordx4 v[94:97], v[102:103], off
	global_load_dwordx4 v[90:93], v[102:103], off offset:64
	global_load_dwordx4 v[86:89], v[102:103], off offset:512
	global_load_dwordx4 v[82:85], v[102:103], off offset:576
	v_lshlrev_b64 v[120:121], 11, v[120:121]
	v_lshl_add_u64 v[120:121], v[120:121], 0, v[182:183]
	s_waitcnt vmcnt(7)
	v_pk_fma_f32 v[80:81], v[80:81], v[64:65], v[110:111]
	v_pk_fma_f32 v[78:79], v[78:79], v[62:63], v[108:109]
	v_mul_f32_e32 v109, v81, v81
	v_mul_f32_e32 v108, v79, v79
	global_store_dwordx4 v[106:107], v[78:81], off
	v_fmac_f32_e32 v108, v78, v78
	v_fmac_f32_e32 v109, v80, v80
	v_pk_mul_f32 v[80:81], v[196:197], v[80:81]
	v_pk_mul_f32 v[78:79], v[198:199], v[78:79]
	s_waitcnt vmcnt(7)
	v_pk_fma_f32 v[74:75], v[74:75], v[58:59], v[112:113]
	v_add_f32_e32 v110, v108, v109
	v_cvt_pk_bf16_f32 v240, v78, v79
	v_cvt_pk_bf16_f32 v241, v80, v81
	v_lshl_add_u64 v[78:79], v[120:121], 1, s[50:51]
	v_pk_fma_f32 v[76:77], v[76:77], v[60:61], v[114:115]
	v_mul_f32_e32 v80, v75, v75
	global_store_dwordx4 v[106:107], v[74:77], off offset:64
	v_fmac_f32_e32 v80, v74, v74
	v_mul_f32_e32 v81, v77, v77
	v_pk_mul_f32 v[74:75], v[194:195], v[74:75]
	s_waitcnt vmcnt(7)
	v_pk_fma_f32 v[70:71], v[70:71], v[54:55], v[116:117]
	v_cvt_pk_bf16_f32 v242, v74, v75
	v_fmac_f32_e32 v81, v76, v76
	v_pk_mul_f32 v[76:77], v[192:193], v[76:77]
	v_pk_fma_f32 v[72:73], v[72:73], v[56:57], v[118:119]
	v_cvt_pk_bf16_f32 v243, v76, v77
	v_lshl_add_u64 v[252:253], v[236:237], 0, v[78:79]
	s_nop 0
	v_permlane16_swap_b32_e32 v240, v242
	v_permlane16_swap_b32_e32 v241, v243
	global_store_dwordx4 v[252:253], v[240:243], off
	s_nop 1
	v_mul_f32_e32 v74, v71, v71
	global_store_dwordx4 v[106:107], v[70:73], off offset:512
	v_fmac_f32_e32 v74, v70, v70
	v_mul_f32_e32 v75, v73, v73
	v_pk_mul_f32 v[70:71], v[190:191], v[70:71]
	v_fmac_f32_e32 v75, v72, v72
	v_pk_mul_f32 v[72:73], v[188:189], v[72:73]
	v_cvt_pk_bf16_f32 v240, v70, v71
	s_waitcnt vmcnt(8)
	v_pk_fma_f32 v[68:69], v[68:69], v[52:53], v[100:101]
	v_cvt_pk_bf16_f32 v241, v72, v73
	v_pk_fma_f32 v[66:67], v[66:67], v[50:51], v[98:99]
	v_add_f32_e32 v80, v80, v81
	v_mul_f32_e32 v70, v67, v67
	v_mul_f32_e32 v71, v69, v69
	v_add_f32_e32 v80, v110, v80
	v_add_f32_e32 v74, v74, v75
	v_fmac_f32_e32 v70, v66, v66
	v_fmac_f32_e32 v71, v68, v68
	v_add_f32_e32 v74, v80, v74
	global_store_dwordx4 v[106:107], v[66:69], off offset:576
	v_add_f32_e32 v70, v70, v71
	v_add_f32_e32 v70, v74, v70
	v_pk_mul_f32 v[66:67], v[184:185], v[66:67]
	v_pk_mul_f32 v[68:69], v[186:187], v[68:69]
	v_cvt_pk_bf16_f32 v242, v66, v67
	s_nop 0
	v_cvt_pk_bf16_f32 v243, v68, v69
	v_lshl_add_u64 v[252:253], v[236:237], 0, v[78:79]
	s_nop 0
	v_permlane16_swap_b32_e32 v240, v242
	v_permlane16_swap_b32_e32 v241, v243
	global_store_dwordx4 v[252:253], v[240:243], off offset:256
	s_nop 1
	ds_swizzle_b32 v66, v70 offset:swizzle(SWAP,16)
	s_waitcnt lgkmcnt(0)
	v_add_f32_e32 v66, v70, v66
	v_mov_b32_e32 v67, v66
	s_nop 1
	v_permlane32_swap_b32_e32 v66, v67
	s_and_saveexec_b64 s[4:5], s[36:37]
	s_cbranch_execz .LBB0_1511
	v_lshl_add_u64 v[68:69], v[180:181], 2, s[52:53]
	v_add_f32_e32 v66, v66, v67
	global_atomic_add_f32 v[68:69], v66, off offset:512
; __device__ __forceinline__ unsigned cvt_pk_bf16(float lo, float hi) { unsigned r; asm volatile("v_cvt_pk_bf16_f32 %0, %1, %2" : "=v"(r) : "v"(lo), "v"(hi)); return r; }
; template <int O> __device__ __forceinline__ float swz_xor(float v) { return __int_as_float(__builtin_amdgcn_ds_swizzle(__float_as_int(v), (O << 10) | 0x1F)); }
;     __device__ __forceinline__ void operator()(const f32x4 (&acc)[2][2][4][2], const Unit& u, int wr, int wc, int fr, int fq) const {
;     ...
;             for (int mm = 0; mm < 2; ++mm) { const int m = 2 * mp + mm; const int row = row0 + ai * HALF + m * 16; const size_t off = (size_t)row * DM + col0; float ss = 0.f;
; #pragma unroll
;                 for (int bj = 0; bj < 2; ++bj)
; #pragma unroll
;                     for (int n = 0; n < 2; ++n) { const f32x4 xn = bs[mm][bj][n] + gv[bj][n] * acc[ai][bj][m][n];
;                         if (RES_BF16) { u32x2 w_; w_.x = cvt_pk_bf16(xn[0], xn[1]); w_.y = cvt_pk_bf16(xn[2], xn[3]); STG(u32x2, xres + off + bj * HALF + n * 16) = w_; }
;                         else STG(f32x4, out + off + bj * HALF + n * 16) = xn;
;                         if (NEXT) { ss += (xn[0] * xn[0] + xn[1] * xn[1]) + (xn[2] * xn[2] + xn[3] * xn[3]); const f32x4 y = xn * gg[bj][n];
;                             u32x2 w; w.x = cvt_pk_bf16(y[0], y[1]); w.y = cvt_pk_bf16(y[2], y[3]); STG(u32x2, xg + off + bj * HALF + n * 16) = w; } }
;                 if (NEXT) { ss += swz_xor<16>(ss); auto rr = __builtin_amdgcn_permlane32_swap(__float_as_uint(ss), __float_as_uint(ss), false, false); ss = __uint_as_float(rr[0]) + __uint_as_float(rr[1]);
;                     if (fq == 0) atomicAdd(ssq + row, ss); } }
.LBB0_1511:
	s_or_b64 exec, exec, s[4:5]
	s_waitcnt vmcnt(9)
	v_pk_fma_f32 v[48:49], v[48:49], v[64:65], v[96:97]
	v_pk_fma_f32 v[46:47], v[46:47], v[62:63], v[94:95]
	v_lshlrev_b64 v[66:67], 11, v[104:105]
	v_mul_f32_e32 v68, v47, v47
	v_mul_f32_e32 v69, v49, v49
	v_lshl_add_u64 v[66:67], v[66:67], 0, v[182:183]
	global_store_dwordx4 v[102:103], v[46:49], off
	v_fmac_f32_e32 v68, v46, v46
	v_fmac_f32_e32 v69, v48, v48
	v_pk_mul_f32 v[48:49], v[196:197], v[48:49]
	v_pk_mul_f32 v[46:47], v[198:199], v[46:47]
	s_waitcnt vmcnt(9)
	v_pk_fma_f32 v[42:43], v[42:43], v[58:59], v[90:91]
	v_cvt_pk_bf16_f32 v240, v46, v47
	v_cvt_pk_bf16_f32 v241, v48, v49
	v_lshl_add_u64 v[48:49], v[66:67], 1, s[50:51]
	v_pk_fma_f32 v[44:45], v[44:45], v[60:61], v[92:93]
	v_mul_f32_e32 v46, v43, v43
	global_store_dwordx4 v[102:103], v[42:45], off offset:64
	v_fmac_f32_e32 v46, v42, v42
	v_mul_f32_e32 v47, v45, v45
	v_pk_mul_f32 v[42:43], v[194:195], v[42:43]
	s_waitcnt vmcnt(9)
	v_pk_fma_f32 v[38:39], v[38:39], v[54:55], v[86:87]
	v_cvt_pk_bf16_f32 v242, v42, v43
	v_fmac_f32_e32 v47, v44, v44
	v_pk_mul_f32 v[44:45], v[192:193], v[44:45]
	v_pk_fma_f32 v[40:41], v[40:41], v[56:57], v[88:89]
	v_cvt_pk_bf16_f32 v243, v44, v45
	v_lshl_add_u64 v[252:253], v[236:237], 0, v[48:49]
	s_nop 0
	v_permlane16_swap_b32_e32 v240, v242
	v_permlane16_swap_b32_e32 v241, v243
	global_store_dwordx4 v[252:253], v[240:243], off
	s_nop 1
	v_mul_f32_e32 v42, v39, v39
	global_store_dwordx4 v[102:103], v[38:41], off offset:512
	v_fmac_f32_e32 v42, v38, v38
	v_mul_f32_e32 v43, v41, v41
	v_pk_mul_f32 v[38:39], v[190:191], v[38:39]
	v_fmac_f32_e32 v43, v40, v40
	v_pk_mul_f32 v[40:41], v[188:189], v[40:41]
	v_cvt_pk_bf16_f32 v240, v38, v39
	s_waitcnt vmcnt(10)
	v_pk_fma_f32 v[36:37], v[36:37], v[52:53], v[84:85]
	v_cvt_pk_bf16_f32 v241, v40, v41
	v_pk_fma_f32 v[34:35], v[34:35], v[50:51], v[82:83]
	v_add_f32_e32 v68, v68, v69
	v_add_f32_e32 v46, v46, v47
	v_mul_f32_e32 v38, v35, v35
	v_mul_f32_e32 v39, v37, v37
	v_add_f32_e32 v46, v68, v46
	v_add_f32_e32 v42, v42, v43
	v_fmac_f32_e32 v38, v34, v34
	v_fmac_f32_e32 v39, v36, v36
	v_add_f32_e32 v42, v46, v42
	v_add_f32_e32 v38, v38, v39
	v_add_f32_e32 v38, v42, v38
	ds_swizzle_b32 v39, v38 offset:swizzle(SWAP,16)
	global_store_dwordx4 v[102:103], v[34:37], off offset:576
	s_nop 1
	v_pk_mul_f32 v[34:35], v[184:185], v[34:35]
	v_pk_mul_f32 v[36:37], v[186:187], v[36:37]
	v_cvt_pk_bf16_f32 v242, v34, v35
	s_nop 0
	v_cvt_pk_bf16_f32 v243, v36, v37
	v_lshl_add_u64 v[252:253], v[236:237], 0, v[48:49]
	s_nop 0
	v_permlane16_swap_b32_e32 v240, v242
	v_permlane16_swap_b32_e32 v241, v243
	global_store_dwordx4 v[252:253], v[240:243], off offset:256
	s_nop 1
	s_waitcnt lgkmcnt(0)
	v_add_f32_e32 v34, v38, v39
	v_mov_b32_e32 v35, v34
	s_nop 1
	v_permlane32_swap_b32_e32 v34, v35
	s_and_saveexec_b64 s[4:5], s[36:37]
	s_cbranch_execz .LBB0_1513
	v_lshl_add_u64 v[36:37], v[180:181], 2, s[52:53]
	v_add_f32_e32 v34, v34, v35
	global_atomic_add_f32 v[36:37], v34, off offset:576
; __device__ __forceinline__ unsigned cvt_pk_bf16(float lo, float hi) { unsigned r; asm volatile("v_cvt_pk_bf16_f32 %0, %1, %2" : "=v"(r) : "v"(lo), "v"(hi)); return r; }
; __device__ __forceinline__ float bf_lo(unsigned w) { return __uint_as_float(w << 16); }
; __device__ __forceinline__ float bf_hi(unsigned w) { return __uint_as_float(w & 0xffff0000u); }
; template <int O> __device__ __forceinline__ float swz_xor(float v) { return __int_as_float(__builtin_amdgcn_ds_swizzle(__float_as_int(v), (O << 10) | 0x1F)); }
;     __device__ __forceinline__ void operator()(const f32x4 (&acc)[2][2][4][2], const Unit& u, int wr, int wc, int fr, int fq) const {
;     ...
;                     for (int n = 0; n < 2; ++n) { const size_t o_ = (size_t)(row0 + ai * HALF + (2 * mp + mm) * 16) * DM + col0 + bj * HALF + n * 16;
;                         if (ai == 0 && mp == 0) bs[mm][bj][n] = bs0[mm][bj][n];
;                         else if (RES_BF16) { const u32x2 r = LDG(u32x2, xres + o_); bs[mm][bj][n] = (f32x4){bf_lo(r.x), bf_hi(r.x), bf_lo(r.y), bf_hi(r.y)}; }
;                         else bs[mm][bj][n] = LDG(f32x4, base + o_); }
;             asm volatile("" ::: "memory");
; #pragma unroll
;             for (int mm = 0; mm < 2; ++mm) { const int m = 2 * mp + mm; const int row = row0 + ai * HALF + m * 16; const size_t off = (size_t)row * DM + col0; float ss = 0.f;
; #pragma unroll
;                 for (int bj = 0; bj < 2; ++bj)
; #pragma unroll
;                     for (int n = 0; n < 2; ++n) { const f32x4 xn = bs[mm][bj][n] + gv[bj][n] * acc[ai][bj][m][n];
;                         if (RES_BF16) { u32x2 w_; w_.x = cvt_pk_bf16(xn[0], xn[1]); w_.y = cvt_pk_bf16(xn[2], xn[3]); STG(u32x2, xres + off + bj * HALF + n * 16) = w_; }
;                         else STG(f32x4, out + off + bj * HALF + n * 16) = xn;
;                         if (NEXT) { ss += (xn[0] * xn[0] + xn[1] * xn[1]) + (xn[2] * xn[2] + xn[3] * xn[3]); const f32x4 y = xn * gg[bj][n];
;                             u32x2 w; w.x = cvt_pk_bf16(y[0], y[1]); w.y = cvt_pk_bf16(y[2], y[3]); STG(u32x2, xg + off + bj * HALF + n * 16) = w; } }
;                 if (NEXT) { ss += swz_xor<16>(ss); auto rr = __builtin_amdgcn_permlane32_swap(__float_as_uint(ss), __float_as_uint(ss), false, false); ss = __uint_as_float(rr[0]) + __uint_as_float(rr[1]);
;                     if (fq == 0) atomicAdd(ssq + row, ss); } }
.LBB0_1513:
	s_or_b64 exec, exec, s[4:5]
	v_add_u32_e32 v88, 0xa0, v180
	v_ashrrev_i32_e32 v89, 31, v88
	v_lshlrev_b64 v[34:35], 13, v[88:89]
	v_lshl_add_u64 v[74:75], v[200:201], 0, v[34:35]
	global_load_dwordx4 v[76:79], v[74:75], off
	global_load_dwordx4 v[80:83], v[74:75], off offset:64
	global_load_dwordx4 v[84:87], v[74:75], off offset:512
	global_load_dwordx4 v[66:69], v[74:75], off offset:576
	v_add_u32_e32 v72, 0xb0, v180
	v_ashrrev_i32_e32 v73, 31, v72
	v_lshlrev_b64 v[34:35], 13, v[72:73]
	v_lshl_add_u64 v[70:71], v[200:201], 0, v[34:35]
	global_load_dwordx4 v[46:49], v[70:71], off
	global_load_dwordx4 v[42:45], v[70:71], off offset:64
	global_load_dwordx4 v[38:41], v[70:71], off offset:512
	global_load_dwordx4 v[34:37], v[70:71], off offset:576
	v_lshlrev_b64 v[88:89], 11, v[88:89]
	v_lshl_add_u64 v[88:89], v[88:89], 0, v[182:183]
	s_waitcnt vmcnt(7)
	v_pk_fma_f32 v[32:33], v[32:33], v[64:65], v[78:79]
	v_pk_fma_f32 v[30:31], v[30:31], v[62:63], v[76:77]
	v_mul_f32_e32 v77, v33, v33
	v_mul_f32_e32 v76, v31, v31
	global_store_dwordx4 v[74:75], v[30:33], off
	v_fmac_f32_e32 v76, v30, v30
	v_fmac_f32_e32 v77, v32, v32
	v_pk_mul_f32 v[32:33], v[196:197], v[32:33]
	v_pk_mul_f32 v[30:31], v[198:199], v[30:31]
	s_waitcnt vmcnt(7)
	v_pk_fma_f32 v[26:27], v[26:27], v[58:59], v[80:81]
	v_add_f32_e32 v78, v76, v77
	v_cvt_pk_bf16_f32 v240, v30, v31
	v_cvt_pk_bf16_f32 v241, v32, v33
	v_lshl_add_u64 v[30:31], v[88:89], 1, s[50:51]
	v_pk_fma_f32 v[28:29], v[28:29], v[60:61], v[82:83]
	v_mul_f32_e32 v32, v27, v27
	global_store_dwordx4 v[74:75], v[26:29], off offset:64
	v_fmac_f32_e32 v32, v26, v26
	v_mul_f32_e32 v33, v29, v29
	v_pk_mul_f32 v[26:27], v[194:195], v[26:27]
	s_waitcnt vmcnt(7)
	v_pk_fma_f32 v[22:23], v[22:23], v[54:55], v[84:85]
	v_cvt_pk_bf16_f32 v242, v26, v27
	v_fmac_f32_e32 v33, v28, v28
	v_pk_mul_f32 v[28:29], v[192:193], v[28:29]
	v_pk_fma_f32 v[24:25], v[24:25], v[56:57], v[86:87]
	v_cvt_pk_bf16_f32 v243, v28, v29
	v_lshl_add_u64 v[252:253], v[236:237], 0, v[30:31]
	s_nop 0
	v_permlane16_swap_b32_e32 v240, v242
	v_permlane16_swap_b32_e32 v241, v243
	global_store_dwordx4 v[252:253], v[240:243], off
	s_nop 1
	v_mul_f32_e32 v26, v23, v23
	global_store_dwordx4 v[74:75], v[22:25], off offset:512
	v_fmac_f32_e32 v26, v22, v22
	v_mul_f32_e32 v27, v25, v25
	v_pk_mul_f32 v[22:23], v[190:191], v[22:23]
	v_fmac_f32_e32 v27, v24, v24
	v_pk_mul_f32 v[24:25], v[188:189], v[24:25]
	v_cvt_pk_bf16_f32 v240, v22, v23
	s_waitcnt vmcnt(8)
	v_pk_fma_f32 v[20:21], v[20:21], v[52:53], v[68:69]
	v_cvt_pk_bf16_f32 v241, v24, v25
	v_pk_fma_f32 v[18:19], v[18:19], v[50:51], v[66:67]
	v_add_f32_e32 v32, v32, v33
	v_mul_f32_e32 v22, v19, v19
	v_mul_f32_e32 v23, v21, v21
	v_add_f32_e32 v32, v78, v32
	v_add_f32_e32 v26, v26, v27
	v_fmac_f32_e32 v22, v18, v18
	v_fmac_f32_e32 v23, v20, v20
	v_add_f32_e32 v26, v32, v26
	global_store_dwordx4 v[74:75], v[18:21], off offset:576
	v_add_f32_e32 v22, v22, v23
	v_add_f32_e32 v22, v26, v22
	v_pk_mul_f32 v[18:19], v[184:185], v[18:19]
	v_pk_mul_f32 v[20:21], v[186:187], v[20:21]
	v_cvt_pk_bf16_f32 v242, v18, v19
	s_nop 0
	v_cvt_pk_bf16_f32 v243, v20, v21
	v_lshl_add_u64 v[252:253], v[236:237], 0, v[30:31]
	s_nop 0
	v_permlane16_swap_b32_e32 v240, v242
	v_permlane16_swap_b32_e32 v241, v243
	global_store_dwordx4 v[252:253], v[240:243], off offset:256
	s_nop 1
	ds_swizzle_b32 v18, v22 offset:swizzle(SWAP,16)
	s_waitcnt lgkmcnt(0)
	v_add_f32_e32 v18, v22, v18
	v_mov_b32_e32 v19, v18
	s_nop 1
	v_permlane32_swap_b32_e32 v18, v19
	s_and_saveexec_b64 s[4:5], s[36:37]
	s_cbranch_execz .LBB0_1515
	v_lshl_add_u64 v[20:21], v[180:181], 2, s[52:53]
	v_add_f32_e32 v18, v18, v19
	global_atomic_add_f32 v[20:21], v18, off offset:640
.LBB0_1515:
	s_or_b64 exec, exec, s[4:5]
	s_waitcnt vmcnt(9)
	v_pk_fma_f32 v[16:17], v[16:17], v[64:65], v[48:49]
	v_pk_fma_f32 v[14:15], v[14:15], v[62:63], v[46:47]
	v_lshlrev_b64 v[18:19], 11, v[72:73]
	v_mul_f32_e32 v20, v15, v15
	v_mul_f32_e32 v21, v17, v17
	v_lshl_add_u64 v[18:19], v[18:19], 0, v[182:183]
	global_store_dwordx4 v[70:71], v[14:17], off
	v_fmac_f32_e32 v20, v14, v14
	v_fmac_f32_e32 v21, v16, v16
	v_pk_mul_f32 v[16:17], v[196:197], v[16:17]
	v_pk_mul_f32 v[14:15], v[198:199], v[14:15]
	s_waitcnt vmcnt(9)
	v_pk_fma_f32 v[10:11], v[10:11], v[58:59], v[42:43]
	v_cvt_pk_bf16_f32 v240, v14, v15
	v_cvt_pk_bf16_f32 v241, v16, v17
	v_lshl_add_u64 v[16:17], v[18:19], 1, s[50:51]
	v_pk_fma_f32 v[12:13], v[12:13], v[60:61], v[44:45]
	v_mul_f32_e32 v14, v11, v11
	global_store_dwordx4 v[70:71], v[10:13], off offset:64
	v_fmac_f32_e32 v14, v10, v10
	v_mul_f32_e32 v15, v13, v13
	v_pk_mul_f32 v[10:11], v[194:195], v[10:11]
	s_waitcnt vmcnt(9)
	v_pk_fma_f32 v[6:7], v[6:7], v[54:55], v[38:39]
	v_cvt_pk_bf16_f32 v242, v10, v11
	v_fmac_f32_e32 v15, v12, v12
	v_pk_mul_f32 v[12:13], v[192:193], v[12:13]
	v_pk_fma_f32 v[8:9], v[8:9], v[56:57], v[40:41]
	v_cvt_pk_bf16_f32 v243, v12, v13
	v_lshl_add_u64 v[252:253], v[236:237], 0, v[16:17]
	s_nop 0
	v_permlane16_swap_b32_e32 v240, v242
	v_permlane16_swap_b32_e32 v241, v243
	global_store_dwordx4 v[252:253], v[240:243], off
	s_nop 1
	v_mul_f32_e32 v10, v7, v7
	global_store_dwordx4 v[70:71], v[6:9], off offset:512
	v_fmac_f32_e32 v10, v6, v6
	v_mul_f32_e32 v11, v9, v9
	v_pk_mul_f32 v[6:7], v[190:191], v[6:7]
	v_fmac_f32_e32 v11, v8, v8
	v_pk_mul_f32 v[8:9], v[188:189], v[8:9]
	v_cvt_pk_bf16_f32 v240, v6, v7
	s_waitcnt vmcnt(10)
	v_pk_fma_f32 v[4:5], v[4:5], v[52:53], v[36:37]
	v_cvt_pk_bf16_f32 v241, v8, v9
	v_pk_fma_f32 v[2:3], v[2:3], v[50:51], v[34:35]
	v_add_f32_e32 v20, v20, v21
	v_add_f32_e32 v14, v14, v15
	v_mul_f32_e32 v6, v3, v3
	v_mul_f32_e32 v7, v5, v5
	v_add_f32_e32 v14, v20, v14
	v_add_f32_e32 v10, v10, v11
	v_fmac_f32_e32 v6, v2, v2
	v_fmac_f32_e32 v7, v4, v4
	v_add_f32_e32 v10, v14, v10
	v_add_f32_e32 v6, v6, v7
	v_add_f32_e32 v6, v10, v6
	ds_swizzle_b32 v7, v6 offset:swizzle(SWAP,16)
	global_store_dwordx4 v[70:71], v[2:5], off offset:576
	s_nop 1
	v_pk_mul_f32 v[2:3], v[184:185], v[2:3]
	v_pk_mul_f32 v[4:5], v[186:187], v[4:5]
	v_cvt_pk_bf16_f32 v242, v2, v3
	s_nop 0
	v_cvt_pk_bf16_f32 v243, v4, v5
	v_lshl_add_u64 v[252:253], v[236:237], 0, v[16:17]
	s_nop 0
	v_permlane16_swap_b32_e32 v240, v242
	v_permlane16_swap_b32_e32 v241, v243
	global_store_dwordx4 v[252:253], v[240:243], off offset:256
	s_nop 1
	s_waitcnt lgkmcnt(0)
	v_add_f32_e32 v2, v6, v7
	v_mov_b32_e32 v3, v2
	s_nop 1
	v_permlane32_swap_b32_e32 v2, v3
	s_and_saveexec_b64 s[4:5], s[36:37]
	s_cbranch_execz .LBB0_1517
	v_lshl_add_u64 v[4:5], v[180:181], 2, s[52:53]
	v_add_f32_e32 v2, v2, v3
	global_atomic_add_f32 v[4:5], v2, off offset:704
